# nsa_tile_write_immediate_offsets_and_finer_ranking_exit
# baseline (speedup 1.0000x reference)
.LBB0_579:
	s_or_b64 exec, exec, s[2:3]
	v_add_u32_e32 v43, s14, v41
	s_waitcnt lgkmcnt(0)
	v_add_f32_e32 v32, v32, v33
	v_ashrrev_i32_e32 v43, 6, v43
	v_add_f32_e32 v32, v32, v34
	v_add_u32_e32 v44, -1, v43
	v_fmac_f32_e32 v32, 0.5, v35
	v_cmp_eq_u32_e64 s[0:1], v38, v43
	v_add_f32_e32 v32, v32, v42
	s_or_b64 s[0:1], vcc, s[0:1]
	v_cmp_eq_u32_e32 vcc, v38, v44
	v_add_f32_e32 v33, 0x447a0000, v32
	s_or_b64 vcc, s[0:1], vcc
	v_lshlrev_b32_e32 v41, 8, v41
	v_cndmask_b32_e32 v32, v32, v33, vcc
	v_cmp_le_i32_e32 vcc, v38, v43
	v_lshlrev_b32_e32 v33, 2, v38
	v_readlane_b32 s2, v254, 8
	v_or_b32_e32 v42, 16, v38
	v_cndmask_b32_e32 v32, -1.0, v32, vcc
	v_add3_u32 v41, s2, v41, v33
	v_lshl_add_u32 v45, v42, 4, v40
	ds_write_b32 v41, v32
	v_add_u32_e32 v32, -4, v45
	ds_read2_b32 v[32:33], v32 offset1:1
	ds_read2_b32 v[34:35], v45 offset0:1 offset1:2
	ds_read_b32 v45, v45 offset:12
	v_cmp_eq_u32_e32 vcc, v42, v43
	v_cmp_eq_u32_e64 s[0:1], v42, v44
	s_or_b64 vcc, vcc, s[0:1]
	s_waitcnt lgkmcnt(1)
	v_add_f32_e32 v33, v33, v34
	v_add_f32_e32 v33, v33, v35
	s_waitcnt lgkmcnt(0)
	v_fmac_f32_e32 v33, 0.5, v45
	v_fmac_f32_e32 v33, 0.5, v32
	v_add_f32_e32 v32, 0x447a0000, v33
	v_cndmask_b32_e32 v32, v33, v32, vcc
	v_cmp_le_i32_e32 vcc, v42, v43
	v_or_b32_e32 v42, 32, v38
	v_lshl_add_u32 v45, v42, 4, v40
	v_cndmask_b32_e32 v32, -1.0, v32, vcc
	ds_write_b32 v41, v32 offset:64
	v_add_u32_e32 v32, -4, v45
	ds_read2_b32 v[32:33], v32 offset1:1
	ds_read2_b32 v[34:35], v45 offset0:1 offset1:2
	ds_read_b32 v45, v45 offset:12
	v_cmp_eq_u32_e32 vcc, v42, v43
	v_cmp_eq_u32_e64 s[0:1], v42, v44
	s_or_b64 vcc, vcc, s[0:1]
	s_waitcnt lgkmcnt(1)
	v_add_f32_e32 v33, v33, v34
	v_add_f32_e32 v33, v33, v35
	s_waitcnt lgkmcnt(0)
	v_fmac_f32_e32 v33, 0.5, v45
	v_fmac_f32_e32 v33, 0.5, v32
	v_add_f32_e32 v32, 0x447a0000, v33
	v_cndmask_b32_e32 v32, v33, v32, vcc
	v_cmp_le_i32_e32 vcc, v42, v43
	v_or_b32_e32 v42, 48, v38
	v_lshl_add_u32 v40, v42, 4, v40
	v_cndmask_b32_e32 v32, -1.0, v32, vcc
	ds_write_b32 v41, v32 offset:128
	v_add_u32_e32 v32, -4, v40
	ds_read2_b32 v[32:33], v32 offset1:1
	ds_read2_b32 v[34:35], v40 offset0:1 offset1:2
	ds_read_b32 v40, v40 offset:12
	v_cmp_eq_u32_e32 vcc, v42, v43
	v_cmp_eq_u32_e64 s[0:1], v42, v44
	s_or_b64 vcc, vcc, s[0:1]
	s_waitcnt lgkmcnt(1)
	v_add_f32_e32 v33, v33, v34
	v_add_f32_e32 v33, v33, v35
	s_waitcnt lgkmcnt(0)
	v_fmac_f32_e32 v33, 0.5, v40
	v_fmac_f32_e32 v33, 0.5, v32
	v_add_f32_e32 v32, 0x447a0000, v33
	v_cndmask_b32_e32 v32, v33, v32, vcc
	v_cmp_le_i32_e32 vcc, v42, v43
	s_lshl_b32 s0, s15, 8
	s_add_i32 s0, s2, s0
	v_cndmask_b32_e32 v32, -1.0, v32, vcc
	s_or_b32 s12, s15, 2
	ds_write_b32 v41, v32 offset:192
	v_add_u32_e32 v32, s0, v117
	s_lshl_b32 s0, s12, 8
	s_waitcnt lgkmcnt(0)
	s_barrier
	ds_read2st64_b32 v[32:33], v32 offset1:1
	s_add_i32 s0, s2, s0
	v_add_u32_e32 v34, s0, v117
	v_readlane_b32 s0, v254, 33
	s_or_b32 s13, s0, 3
	s_lshl_b32 s0, s13, 8
	s_add_i32 s0, s2, s0
	v_add_u32_e32 v40, s0, v117
	ds_read_b32 v35, v34
	ds_read_b32 v34, v40
	s_waitcnt lgkmcnt(0)
	s_lshr_b32 s30, s14, 6
	v_mov_b32_e32 v40, 0
	v_mov_b32_e32 v41, 0
	v_mov_b32_e32 v42, 0
	v_mov_b32_e32 v43, 0
	v_readlane_b32 s0, v32, 0
	v_readlane_b32 s1, v33, 0
	v_readlane_b32 s2, v35, 0
	v_readlane_b32 s3, v34, 0
	s_lshl_b64 s[26:27], -1, 1
	v_cmp_gt_f32_e64 s[4:5], s0, v32
	v_cmp_gt_f32_e64 s[6:7], s1, v33
	v_cmp_gt_f32_e64 s[8:9], s2, v35
	v_cmp_gt_f32_e64 s[16:17], s3, v34
	v_cmp_eq_f32_e64 s[18:19], s0, v32
	v_cmp_eq_f32_e64 s[20:21], s1, v33
	v_cmp_eq_f32_e64 s[22:23], s2, v35
	v_cmp_eq_f32_e64 s[24:25], s3, v34
	s_and_b64 s[18:19], s[18:19], s[26:27]
	s_or_b64 s[4:5], s[4:5], s[18:19]
	s_and_b64 s[20:21], s[20:21], s[26:27]
	s_or_b64 s[6:7], s[6:7], s[20:21]
	s_and_b64 s[22:23], s[22:23], s[26:27]
	s_or_b64 s[8:9], s[8:9], s[22:23]
	s_and_b64 s[24:25], s[24:25], s[26:27]
	s_or_b64 s[16:17], s[16:17], s[24:25]
	v_addc_co_u32_e64 v40, s[28:29], 0, v40, s[4:5]
	v_addc_co_u32_e64 v41, s[28:29], 0, v41, s[6:7]
	v_addc_co_u32_e64 v42, s[28:29], 0, v42, s[8:9]
	v_addc_co_u32_e64 v43, s[28:29], 0, v43, s[16:17]
	v_readlane_b32 s0, v32, 1
	v_readlane_b32 s1, v33, 1
	v_readlane_b32 s2, v35, 1
	v_readlane_b32 s3, v34, 1
	s_lshl_b64 s[26:27], -1, 2
	v_cmp_gt_f32_e64 s[4:5], s0, v32
	v_cmp_gt_f32_e64 s[6:7], s1, v33
	v_cmp_gt_f32_e64 s[8:9], s2, v35
	v_cmp_gt_f32_e64 s[16:17], s3, v34
	v_cmp_eq_f32_e64 s[18:19], s0, v32
	v_cmp_eq_f32_e64 s[20:21], s1, v33
	v_cmp_eq_f32_e64 s[22:23], s2, v35
	v_cmp_eq_f32_e64 s[24:25], s3, v34
	s_and_b64 s[18:19], s[18:19], s[26:27]
	s_or_b64 s[4:5], s[4:5], s[18:19]
	s_and_b64 s[20:21], s[20:21], s[26:27]
	s_or_b64 s[6:7], s[6:7], s[20:21]
	s_and_b64 s[22:23], s[22:23], s[26:27]
	s_or_b64 s[8:9], s[8:9], s[22:23]
	s_and_b64 s[24:25], s[24:25], s[26:27]
	s_or_b64 s[16:17], s[16:17], s[24:25]
	v_addc_co_u32_e64 v40, s[28:29], 0, v40, s[4:5]
	v_addc_co_u32_e64 v41, s[28:29], 0, v41, s[6:7]
	v_addc_co_u32_e64 v42, s[28:29], 0, v42, s[8:9]
	v_addc_co_u32_e64 v43, s[28:29], 0, v43, s[16:17]
	s_cmp_lt_u32 s30, 2
	s_cbranch_scc1 .Lnsa_rank_done
	v_readlane_b32 s0, v32, 2
	v_readlane_b32 s1, v33, 2
	v_readlane_b32 s2, v35, 2
	v_readlane_b32 s3, v34, 2
	s_lshl_b64 s[26:27], -1, 3
	v_cmp_gt_f32_e64 s[4:5], s0, v32
	v_cmp_gt_f32_e64 s[6:7], s1, v33
	v_cmp_gt_f32_e64 s[8:9], s2, v35
	v_cmp_gt_f32_e64 s[16:17], s3, v34
	v_cmp_eq_f32_e64 s[18:19], s0, v32
	v_cmp_eq_f32_e64 s[20:21], s1, v33
	v_cmp_eq_f32_e64 s[22:23], s2, v35
	v_cmp_eq_f32_e64 s[24:25], s3, v34
	s_and_b64 s[18:19], s[18:19], s[26:27]
	s_or_b64 s[4:5], s[4:5], s[18:19]
	s_and_b64 s[20:21], s[20:21], s[26:27]
	s_or_b64 s[6:7], s[6:7], s[20:21]
	s_and_b64 s[22:23], s[22:23], s[26:27]
	s_or_b64 s[8:9], s[8:9], s[22:23]
	s_and_b64 s[24:25], s[24:25], s[26:27]
	s_or_b64 s[16:17], s[16:17], s[24:25]
	v_addc_co_u32_e64 v40, s[28:29], 0, v40, s[4:5]
	v_addc_co_u32_e64 v41, s[28:29], 0, v41, s[6:7]
	v_addc_co_u32_e64 v42, s[28:29], 0, v42, s[8:9]
	v_addc_co_u32_e64 v43, s[28:29], 0, v43, s[16:17]
	v_readlane_b32 s0, v32, 3
	v_readlane_b32 s1, v33, 3
	v_readlane_b32 s2, v35, 3
	v_readlane_b32 s3, v34, 3
	s_lshl_b64 s[26:27], -1, 4
	v_cmp_gt_f32_e64 s[4:5], s0, v32
	v_cmp_gt_f32_e64 s[6:7], s1, v33
	v_cmp_gt_f32_e64 s[8:9], s2, v35
	v_cmp_gt_f32_e64 s[16:17], s3, v34
	v_cmp_eq_f32_e64 s[18:19], s0, v32
	v_cmp_eq_f32_e64 s[20:21], s1, v33
	v_cmp_eq_f32_e64 s[22:23], s2, v35
	v_cmp_eq_f32_e64 s[24:25], s3, v34
	s_and_b64 s[18:19], s[18:19], s[26:27]
	s_or_b64 s[4:5], s[4:5], s[18:19]
	s_and_b64 s[20:21], s[20:21], s[26:27]
	s_or_b64 s[6:7], s[6:7], s[20:21]
	s_and_b64 s[22:23], s[22:23], s[26:27]
	s_or_b64 s[8:9], s[8:9], s[22:23]
	s_and_b64 s[24:25], s[24:25], s[26:27]
	s_or_b64 s[16:17], s[16:17], s[24:25]
	v_addc_co_u32_e64 v40, s[28:29], 0, v40, s[4:5]
	v_addc_co_u32_e64 v41, s[28:29], 0, v41, s[6:7]
	v_addc_co_u32_e64 v42, s[28:29], 0, v42, s[8:9]
	v_addc_co_u32_e64 v43, s[28:29], 0, v43, s[16:17]
	s_cmp_lt_u32 s30, 4
	s_cbranch_scc1 .Lnsa_rank_done
	v_readlane_b32 s0, v32, 4
	v_readlane_b32 s1, v33, 4
	v_readlane_b32 s2, v35, 4
	v_readlane_b32 s3, v34, 4
	s_lshl_b64 s[26:27], -1, 5
	v_cmp_gt_f32_e64 s[4:5], s0, v32
	v_cmp_gt_f32_e64 s[6:7], s1, v33
	v_cmp_gt_f32_e64 s[8:9], s2, v35
	v_cmp_gt_f32_e64 s[16:17], s3, v34
	v_cmp_eq_f32_e64 s[18:19], s0, v32
	v_cmp_eq_f32_e64 s[20:21], s1, v33
	v_cmp_eq_f32_e64 s[22:23], s2, v35
	v_cmp_eq_f32_e64 s[24:25], s3, v34
	s_and_b64 s[18:19], s[18:19], s[26:27]
	s_or_b64 s[4:5], s[4:5], s[18:19]
	s_and_b64 s[20:21], s[20:21], s[26:27]
	s_or_b64 s[6:7], s[6:7], s[20:21]
	s_and_b64 s[22:23], s[22:23], s[26:27]
	s_or_b64 s[8:9], s[8:9], s[22:23]
	s_and_b64 s[24:25], s[24:25], s[26:27]
	s_or_b64 s[16:17], s[16:17], s[24:25]
	v_addc_co_u32_e64 v40, s[28:29], 0, v40, s[4:5]
	v_addc_co_u32_e64 v41, s[28:29], 0, v41, s[6:7]
	v_addc_co_u32_e64 v42, s[28:29], 0, v42, s[8:9]
	v_addc_co_u32_e64 v43, s[28:29], 0, v43, s[16:17]
	v_readlane_b32 s0, v32, 5
	v_readlane_b32 s1, v33, 5
	v_readlane_b32 s2, v35, 5
	v_readlane_b32 s3, v34, 5
	s_lshl_b64 s[26:27], -1, 6
	v_cmp_gt_f32_e64 s[4:5], s0, v32
	v_cmp_gt_f32_e64 s[6:7], s1, v33
	v_cmp_gt_f32_e64 s[8:9], s2, v35
	v_cmp_gt_f32_e64 s[16:17], s3, v34
	v_cmp_eq_f32_e64 s[18:19], s0, v32
	v_cmp_eq_f32_e64 s[20:21], s1, v33
	v_cmp_eq_f32_e64 s[22:23], s2, v35
	v_cmp_eq_f32_e64 s[24:25], s3, v34
	s_and_b64 s[18:19], s[18:19], s[26:27]
	s_or_b64 s[4:5], s[4:5], s[18:19]
	s_and_b64 s[20:21], s[20:21], s[26:27]
	s_or_b64 s[6:7], s[6:7], s[20:21]
	s_and_b64 s[22:23], s[22:23], s[26:27]
	s_or_b64 s[8:9], s[8:9], s[22:23]
	s_and_b64 s[24:25], s[24:25], s[26:27]
	s_or_b64 s[16:17], s[16:17], s[24:25]
	v_addc_co_u32_e64 v40, s[28:29], 0, v40, s[4:5]
	v_addc_co_u32_e64 v41, s[28:29], 0, v41, s[6:7]
	v_addc_co_u32_e64 v42, s[28:29], 0, v42, s[8:9]
	v_addc_co_u32_e64 v43, s[28:29], 0, v43, s[16:17]
	s_cmp_lt_u32 s30, 6
	s_cbranch_scc1 .Lnsa_rank_done
	v_readlane_b32 s0, v32, 6
	v_readlane_b32 s1, v33, 6
	v_readlane_b32 s2, v35, 6
	v_readlane_b32 s3, v34, 6
	s_lshl_b64 s[26:27], -1, 7
	v_cmp_gt_f32_e64 s[4:5], s0, v32
	v_cmp_gt_f32_e64 s[6:7], s1, v33
	v_cmp_gt_f32_e64 s[8:9], s2, v35
	v_cmp_gt_f32_e64 s[16:17], s3, v34
	v_cmp_eq_f32_e64 s[18:19], s0, v32
	v_cmp_eq_f32_e64 s[20:21], s1, v33
	v_cmp_eq_f32_e64 s[22:23], s2, v35
	v_cmp_eq_f32_e64 s[24:25], s3, v34
	s_and_b64 s[18:19], s[18:19], s[26:27]
	s_or_b64 s[4:5], s[4:5], s[18:19]
	s_and_b64 s[20:21], s[20:21], s[26:27]
	s_or_b64 s[6:7], s[6:7], s[20:21]
	s_and_b64 s[22:23], s[22:23], s[26:27]
	s_or_b64 s[8:9], s[8:9], s[22:23]
	s_and_b64 s[24:25], s[24:25], s[26:27]
	s_or_b64 s[16:17], s[16:17], s[24:25]
	v_addc_co_u32_e64 v40, s[28:29], 0, v40, s[4:5]
	v_addc_co_u32_e64 v41, s[28:29], 0, v41, s[6:7]
	v_addc_co_u32_e64 v42, s[28:29], 0, v42, s[8:9]
	v_addc_co_u32_e64 v43, s[28:29], 0, v43, s[16:17]
	v_readlane_b32 s0, v32, 7
	v_readlane_b32 s1, v33, 7
	v_readlane_b32 s2, v35, 7
	v_readlane_b32 s3, v34, 7
	s_lshl_b64 s[26:27], -1, 8
	v_cmp_gt_f32_e64 s[4:5], s0, v32
	v_cmp_gt_f32_e64 s[6:7], s1, v33
	v_cmp_gt_f32_e64 s[8:9], s2, v35
	v_cmp_gt_f32_e64 s[16:17], s3, v34
	v_cmp_eq_f32_e64 s[18:19], s0, v32
	v_cmp_eq_f32_e64 s[20:21], s1, v33
	v_cmp_eq_f32_e64 s[22:23], s2, v35
	v_cmp_eq_f32_e64 s[24:25], s3, v34
	s_and_b64 s[18:19], s[18:19], s[26:27]
	s_or_b64 s[4:5], s[4:5], s[18:19]
	s_and_b64 s[20:21], s[20:21], s[26:27]
	s_or_b64 s[6:7], s[6:7], s[20:21]
	s_and_b64 s[22:23], s[22:23], s[26:27]
	s_or_b64 s[8:9], s[8:9], s[22:23]
	s_and_b64 s[24:25], s[24:25], s[26:27]
	s_or_b64 s[16:17], s[16:17], s[24:25]
	v_addc_co_u32_e64 v40, s[28:29], 0, v40, s[4:5]
	v_addc_co_u32_e64 v41, s[28:29], 0, v41, s[6:7]
	v_addc_co_u32_e64 v42, s[28:29], 0, v42, s[8:9]
	v_addc_co_u32_e64 v43, s[28:29], 0, v43, s[16:17]
	s_cmp_lt_u32 s30, 8
	s_cbranch_scc1 .Lnsa_rank_done
	v_readlane_b32 s0, v32, 8
	v_readlane_b32 s1, v33, 8
	v_readlane_b32 s2, v35, 8
	v_readlane_b32 s3, v34, 8
	s_lshl_b64 s[26:27], -1, 9
	v_cmp_gt_f32_e64 s[4:5], s0, v32
	v_cmp_gt_f32_e64 s[6:7], s1, v33
	v_cmp_gt_f32_e64 s[8:9], s2, v35
	v_cmp_gt_f32_e64 s[16:17], s3, v34
	v_cmp_eq_f32_e64 s[18:19], s0, v32
	v_cmp_eq_f32_e64 s[20:21], s1, v33
	v_cmp_eq_f32_e64 s[22:23], s2, v35
	v_cmp_eq_f32_e64 s[24:25], s3, v34
	s_and_b64 s[18:19], s[18:19], s[26:27]
	s_or_b64 s[4:5], s[4:5], s[18:19]
	s_and_b64 s[20:21], s[20:21], s[26:27]
	s_or_b64 s[6:7], s[6:7], s[20:21]
	s_and_b64 s[22:23], s[22:23], s[26:27]
	s_or_b64 s[8:9], s[8:9], s[22:23]
	s_and_b64 s[24:25], s[24:25], s[26:27]
	s_or_b64 s[16:17], s[16:17], s[24:25]
	v_addc_co_u32_e64 v40, s[28:29], 0, v40, s[4:5]
	v_addc_co_u32_e64 v41, s[28:29], 0, v41, s[6:7]
	v_addc_co_u32_e64 v42, s[28:29], 0, v42, s[8:9]
	v_addc_co_u32_e64 v43, s[28:29], 0, v43, s[16:17]
	v_readlane_b32 s0, v32, 9
	v_readlane_b32 s1, v33, 9
	v_readlane_b32 s2, v35, 9
	v_readlane_b32 s3, v34, 9
	s_lshl_b64 s[26:27], -1, 10
	v_cmp_gt_f32_e64 s[4:5], s0, v32
	v_cmp_gt_f32_e64 s[6:7], s1, v33
	v_cmp_gt_f32_e64 s[8:9], s2, v35
	v_cmp_gt_f32_e64 s[16:17], s3, v34
	v_cmp_eq_f32_e64 s[18:19], s0, v32
	v_cmp_eq_f32_e64 s[20:21], s1, v33
	v_cmp_eq_f32_e64 s[22:23], s2, v35
	v_cmp_eq_f32_e64 s[24:25], s3, v34
	s_and_b64 s[18:19], s[18:19], s[26:27]
	s_or_b64 s[4:5], s[4:5], s[18:19]
	s_and_b64 s[20:21], s[20:21], s[26:27]
	s_or_b64 s[6:7], s[6:7], s[20:21]
	s_and_b64 s[22:23], s[22:23], s[26:27]
	s_or_b64 s[8:9], s[8:9], s[22:23]
	s_and_b64 s[24:25], s[24:25], s[26:27]
	s_or_b64 s[16:17], s[16:17], s[24:25]
	v_addc_co_u32_e64 v40, s[28:29], 0, v40, s[4:5]
	v_addc_co_u32_e64 v41, s[28:29], 0, v41, s[6:7]
	v_addc_co_u32_e64 v42, s[28:29], 0, v42, s[8:9]
	v_addc_co_u32_e64 v43, s[28:29], 0, v43, s[16:17]
	s_cmp_lt_u32 s30, 10
	s_cbranch_scc1 .Lnsa_rank_done
	v_readlane_b32 s0, v32, 10
	v_readlane_b32 s1, v33, 10
	v_readlane_b32 s2, v35, 10
	v_readlane_b32 s3, v34, 10
	s_lshl_b64 s[26:27], -1, 11
	v_cmp_gt_f32_e64 s[4:5], s0, v32
	v_cmp_gt_f32_e64 s[6:7], s1, v33
	v_cmp_gt_f32_e64 s[8:9], s2, v35
	v_cmp_gt_f32_e64 s[16:17], s3, v34
	v_cmp_eq_f32_e64 s[18:19], s0, v32
	v_cmp_eq_f32_e64 s[20:21], s1, v33
	v_cmp_eq_f32_e64 s[22:23], s2, v35
	v_cmp_eq_f32_e64 s[24:25], s3, v34
	s_and_b64 s[18:19], s[18:19], s[26:27]
	s_or_b64 s[4:5], s[4:5], s[18:19]
	s_and_b64 s[20:21], s[20:21], s[26:27]
	s_or_b64 s[6:7], s[6:7], s[20:21]
	s_and_b64 s[22:23], s[22:23], s[26:27]
	s_or_b64 s[8:9], s[8:9], s[22:23]
	s_and_b64 s[24:25], s[24:25], s[26:27]
	s_or_b64 s[16:17], s[16:17], s[24:25]
	v_addc_co_u32_e64 v40, s[28:29], 0, v40, s[4:5]
	v_addc_co_u32_e64 v41, s[28:29], 0, v41, s[6:7]
	v_addc_co_u32_e64 v42, s[28:29], 0, v42, s[8:9]
	v_addc_co_u32_e64 v43, s[28:29], 0, v43, s[16:17]
	v_readlane_b32 s0, v32, 11
	v_readlane_b32 s1, v33, 11
	v_readlane_b32 s2, v35, 11
	v_readlane_b32 s3, v34, 11
	s_lshl_b64 s[26:27], -1, 12
	v_cmp_gt_f32_e64 s[4:5], s0, v32
	v_cmp_gt_f32_e64 s[6:7], s1, v33
	v_cmp_gt_f32_e64 s[8:9], s2, v35
	v_cmp_gt_f32_e64 s[16:17], s3, v34
	v_cmp_eq_f32_e64 s[18:19], s0, v32
	v_cmp_eq_f32_e64 s[20:21], s1, v33
	v_cmp_eq_f32_e64 s[22:23], s2, v35
	v_cmp_eq_f32_e64 s[24:25], s3, v34
	s_and_b64 s[18:19], s[18:19], s[26:27]
	s_or_b64 s[4:5], s[4:5], s[18:19]
	s_and_b64 s[20:21], s[20:21], s[26:27]
	s_or_b64 s[6:7], s[6:7], s[20:21]
	s_and_b64 s[22:23], s[22:23], s[26:27]
	s_or_b64 s[8:9], s[8:9], s[22:23]
	s_and_b64 s[24:25], s[24:25], s[26:27]
	s_or_b64 s[16:17], s[16:17], s[24:25]
	v_addc_co_u32_e64 v40, s[28:29], 0, v40, s[4:5]
	v_addc_co_u32_e64 v41, s[28:29], 0, v41, s[6:7]
	v_addc_co_u32_e64 v42, s[28:29], 0, v42, s[8:9]
	v_addc_co_u32_e64 v43, s[28:29], 0, v43, s[16:17]
	s_cmp_lt_u32 s30, 12
	s_cbranch_scc1 .Lnsa_rank_done
	v_readlane_b32 s0, v32, 12
	v_readlane_b32 s1, v33, 12
	v_readlane_b32 s2, v35, 12
	v_readlane_b32 s3, v34, 12
	s_lshl_b64 s[26:27], -1, 13
	v_cmp_gt_f32_e64 s[4:5], s0, v32
	v_cmp_gt_f32_e64 s[6:7], s1, v33
	v_cmp_gt_f32_e64 s[8:9], s2, v35
	v_cmp_gt_f32_e64 s[16:17], s3, v34
	v_cmp_eq_f32_e64 s[18:19], s0, v32
	v_cmp_eq_f32_e64 s[20:21], s1, v33
	v_cmp_eq_f32_e64 s[22:23], s2, v35
	v_cmp_eq_f32_e64 s[24:25], s3, v34
	s_and_b64 s[18:19], s[18:19], s[26:27]
	s_or_b64 s[4:5], s[4:5], s[18:19]
	s_and_b64 s[20:21], s[20:21], s[26:27]
	s_or_b64 s[6:7], s[6:7], s[20:21]
	s_and_b64 s[22:23], s[22:23], s[26:27]
	s_or_b64 s[8:9], s[8:9], s[22:23]
	s_and_b64 s[24:25], s[24:25], s[26:27]
	s_or_b64 s[16:17], s[16:17], s[24:25]
	v_addc_co_u32_e64 v40, s[28:29], 0, v40, s[4:5]
	v_addc_co_u32_e64 v41, s[28:29], 0, v41, s[6:7]
	v_addc_co_u32_e64 v42, s[28:29], 0, v42, s[8:9]
	v_addc_co_u32_e64 v43, s[28:29], 0, v43, s[16:17]
	v_readlane_b32 s0, v32, 13
	v_readlane_b32 s1, v33, 13
	v_readlane_b32 s2, v35, 13
	v_readlane_b32 s3, v34, 13
	s_lshl_b64 s[26:27], -1, 14
	v_cmp_gt_f32_e64 s[4:5], s0, v32
	v_cmp_gt_f32_e64 s[6:7], s1, v33
	v_cmp_gt_f32_e64 s[8:9], s2, v35
	v_cmp_gt_f32_e64 s[16:17], s3, v34
	v_cmp_eq_f32_e64 s[18:19], s0, v32
	v_cmp_eq_f32_e64 s[20:21], s1, v33
	v_cmp_eq_f32_e64 s[22:23], s2, v35
	v_cmp_eq_f32_e64 s[24:25], s3, v34
	s_and_b64 s[18:19], s[18:19], s[26:27]
	s_or_b64 s[4:5], s[4:5], s[18:19]
	s_and_b64 s[20:21], s[20:21], s[26:27]
	s_or_b64 s[6:7], s[6:7], s[20:21]
	s_and_b64 s[22:23], s[22:23], s[26:27]
	s_or_b64 s[8:9], s[8:9], s[22:23]
	s_and_b64 s[24:25], s[24:25], s[26:27]
	s_or_b64 s[16:17], s[16:17], s[24:25]
	v_addc_co_u32_e64 v40, s[28:29], 0, v40, s[4:5]
	v_addc_co_u32_e64 v41, s[28:29], 0, v41, s[6:7]
	v_addc_co_u32_e64 v42, s[28:29], 0, v42, s[8:9]
	v_addc_co_u32_e64 v43, s[28:29], 0, v43, s[16:17]
	s_cmp_lt_u32 s30, 14
	s_cbranch_scc1 .Lnsa_rank_done
	v_readlane_b32 s0, v32, 14
	v_readlane_b32 s1, v33, 14
	v_readlane_b32 s2, v35, 14
	v_readlane_b32 s3, v34, 14
	s_lshl_b64 s[26:27], -1, 15
	v_cmp_gt_f32_e64 s[4:5], s0, v32
	v_cmp_gt_f32_e64 s[6:7], s1, v33
	v_cmp_gt_f32_e64 s[8:9], s2, v35
	v_cmp_gt_f32_e64 s[16:17], s3, v34
	v_cmp_eq_f32_e64 s[18:19], s0, v32
	v_cmp_eq_f32_e64 s[20:21], s1, v33
	v_cmp_eq_f32_e64 s[22:23], s2, v35
	v_cmp_eq_f32_e64 s[24:25], s3, v34
	s_and_b64 s[18:19], s[18:19], s[26:27]
	s_or_b64 s[4:5], s[4:5], s[18:19]
	s_and_b64 s[20:21], s[20:21], s[26:27]
	s_or_b64 s[6:7], s[6:7], s[20:21]
	s_and_b64 s[22:23], s[22:23], s[26:27]
	s_or_b64 s[8:9], s[8:9], s[22:23]
	s_and_b64 s[24:25], s[24:25], s[26:27]
	s_or_b64 s[16:17], s[16:17], s[24:25]
	v_addc_co_u32_e64 v40, s[28:29], 0, v40, s[4:5]
	v_addc_co_u32_e64 v41, s[28:29], 0, v41, s[6:7]
	v_addc_co_u32_e64 v42, s[28:29], 0, v42, s[8:9]
	v_addc_co_u32_e64 v43, s[28:29], 0, v43, s[16:17]
	v_readlane_b32 s0, v32, 15
	v_readlane_b32 s1, v33, 15
	v_readlane_b32 s2, v35, 15
	v_readlane_b32 s3, v34, 15
	s_lshl_b64 s[26:27], -1, 16
	v_cmp_gt_f32_e64 s[4:5], s0, v32
	v_cmp_gt_f32_e64 s[6:7], s1, v33
	v_cmp_gt_f32_e64 s[8:9], s2, v35
	v_cmp_gt_f32_e64 s[16:17], s3, v34
	v_cmp_eq_f32_e64 s[18:19], s0, v32
	v_cmp_eq_f32_e64 s[20:21], s1, v33
	v_cmp_eq_f32_e64 s[22:23], s2, v35
	v_cmp_eq_f32_e64 s[24:25], s3, v34
	s_and_b64 s[18:19], s[18:19], s[26:27]
	s_or_b64 s[4:5], s[4:5], s[18:19]
	s_and_b64 s[20:21], s[20:21], s[26:27]
	s_or_b64 s[6:7], s[6:7], s[20:21]
	s_and_b64 s[22:23], s[22:23], s[26:27]
	s_or_b64 s[8:9], s[8:9], s[22:23]
	s_and_b64 s[24:25], s[24:25], s[26:27]
	s_or_b64 s[16:17], s[16:17], s[24:25]
	v_addc_co_u32_e64 v40, s[28:29], 0, v40, s[4:5]
	v_addc_co_u32_e64 v41, s[28:29], 0, v41, s[6:7]
	v_addc_co_u32_e64 v42, s[28:29], 0, v42, s[8:9]
	v_addc_co_u32_e64 v43, s[28:29], 0, v43, s[16:17]
	s_cmp_lt_u32 s30, 16
	s_cbranch_scc1 .Lnsa_rank_done
	v_readlane_b32 s0, v32, 16
	v_readlane_b32 s1, v33, 16
	v_readlane_b32 s2, v35, 16
	v_readlane_b32 s3, v34, 16
	s_lshl_b64 s[26:27], -1, 17
	v_cmp_gt_f32_e64 s[4:5], s0, v32
	v_cmp_gt_f32_e64 s[6:7], s1, v33
	v_cmp_gt_f32_e64 s[8:9], s2, v35
	v_cmp_gt_f32_e64 s[16:17], s3, v34
	v_cmp_eq_f32_e64 s[18:19], s0, v32
	v_cmp_eq_f32_e64 s[20:21], s1, v33
	v_cmp_eq_f32_e64 s[22:23], s2, v35
	v_cmp_eq_f32_e64 s[24:25], s3, v34
	s_and_b64 s[18:19], s[18:19], s[26:27]
	s_or_b64 s[4:5], s[4:5], s[18:19]
	s_and_b64 s[20:21], s[20:21], s[26:27]
	s_or_b64 s[6:7], s[6:7], s[20:21]
	s_and_b64 s[22:23], s[22:23], s[26:27]
	s_or_b64 s[8:9], s[8:9], s[22:23]
	s_and_b64 s[24:25], s[24:25], s[26:27]
	s_or_b64 s[16:17], s[16:17], s[24:25]
	v_addc_co_u32_e64 v40, s[28:29], 0, v40, s[4:5]
	v_addc_co_u32_e64 v41, s[28:29], 0, v41, s[6:7]
	v_addc_co_u32_e64 v42, s[28:29], 0, v42, s[8:9]
	v_addc_co_u32_e64 v43, s[28:29], 0, v43, s[16:17]
	v_readlane_b32 s0, v32, 17
	v_readlane_b32 s1, v33, 17
	v_readlane_b32 s2, v35, 17
	v_readlane_b32 s3, v34, 17
	s_lshl_b64 s[26:27], -1, 18
	v_cmp_gt_f32_e64 s[4:5], s0, v32
	v_cmp_gt_f32_e64 s[6:7], s1, v33
	v_cmp_gt_f32_e64 s[8:9], s2, v35
	v_cmp_gt_f32_e64 s[16:17], s3, v34
	v_cmp_eq_f32_e64 s[18:19], s0, v32
	v_cmp_eq_f32_e64 s[20:21], s1, v33
	v_cmp_eq_f32_e64 s[22:23], s2, v35
	v_cmp_eq_f32_e64 s[24:25], s3, v34
	s_and_b64 s[18:19], s[18:19], s[26:27]
	s_or_b64 s[4:5], s[4:5], s[18:19]
	s_and_b64 s[20:21], s[20:21], s[26:27]
	s_or_b64 s[6:7], s[6:7], s[20:21]
	s_and_b64 s[22:23], s[22:23], s[26:27]
	s_or_b64 s[8:9], s[8:9], s[22:23]
	s_and_b64 s[24:25], s[24:25], s[26:27]
	s_or_b64 s[16:17], s[16:17], s[24:25]
	v_addc_co_u32_e64 v40, s[28:29], 0, v40, s[4:5]
	v_addc_co_u32_e64 v41, s[28:29], 0, v41, s[6:7]
	v_addc_co_u32_e64 v42, s[28:29], 0, v42, s[8:9]
	v_addc_co_u32_e64 v43, s[28:29], 0, v43, s[16:17]
	s_cmp_lt_u32 s30, 18
	s_cbranch_scc1 .Lnsa_rank_done
	v_readlane_b32 s0, v32, 18
	v_readlane_b32 s1, v33, 18
	v_readlane_b32 s2, v35, 18
	v_readlane_b32 s3, v34, 18
	s_lshl_b64 s[26:27], -1, 19
	v_cmp_gt_f32_e64 s[4:5], s0, v32
	v_cmp_gt_f32_e64 s[6:7], s1, v33
	v_cmp_gt_f32_e64 s[8:9], s2, v35
	v_cmp_gt_f32_e64 s[16:17], s3, v34
	v_cmp_eq_f32_e64 s[18:19], s0, v32
	v_cmp_eq_f32_e64 s[20:21], s1, v33
	v_cmp_eq_f32_e64 s[22:23], s2, v35
	v_cmp_eq_f32_e64 s[24:25], s3, v34
	s_and_b64 s[18:19], s[18:19], s[26:27]
	s_or_b64 s[4:5], s[4:5], s[18:19]
	s_and_b64 s[20:21], s[20:21], s[26:27]
	s_or_b64 s[6:7], s[6:7], s[20:21]
	s_and_b64 s[22:23], s[22:23], s[26:27]
	s_or_b64 s[8:9], s[8:9], s[22:23]
	s_and_b64 s[24:25], s[24:25], s[26:27]
	s_or_b64 s[16:17], s[16:17], s[24:25]
	v_addc_co_u32_e64 v40, s[28:29], 0, v40, s[4:5]
	v_addc_co_u32_e64 v41, s[28:29], 0, v41, s[6:7]
	v_addc_co_u32_e64 v42, s[28:29], 0, v42, s[8:9]
	v_addc_co_u32_e64 v43, s[28:29], 0, v43, s[16:17]
	v_readlane_b32 s0, v32, 19
	v_readlane_b32 s1, v33, 19
	v_readlane_b32 s2, v35, 19
	v_readlane_b32 s3, v34, 19
	s_lshl_b64 s[26:27], -1, 20
	v_cmp_gt_f32_e64 s[4:5], s0, v32
	v_cmp_gt_f32_e64 s[6:7], s1, v33
	v_cmp_gt_f32_e64 s[8:9], s2, v35
	v_cmp_gt_f32_e64 s[16:17], s3, v34
	v_cmp_eq_f32_e64 s[18:19], s0, v32
	v_cmp_eq_f32_e64 s[20:21], s1, v33
	v_cmp_eq_f32_e64 s[22:23], s2, v35
	v_cmp_eq_f32_e64 s[24:25], s3, v34
	s_and_b64 s[18:19], s[18:19], s[26:27]
	s_or_b64 s[4:5], s[4:5], s[18:19]
	s_and_b64 s[20:21], s[20:21], s[26:27]
	s_or_b64 s[6:7], s[6:7], s[20:21]
	s_and_b64 s[22:23], s[22:23], s[26:27]
	s_or_b64 s[8:9], s[8:9], s[22:23]
	s_and_b64 s[24:25], s[24:25], s[26:27]
	s_or_b64 s[16:17], s[16:17], s[24:25]
	v_addc_co_u32_e64 v40, s[28:29], 0, v40, s[4:5]
	v_addc_co_u32_e64 v41, s[28:29], 0, v41, s[6:7]
	v_addc_co_u32_e64 v42, s[28:29], 0, v42, s[8:9]
	v_addc_co_u32_e64 v43, s[28:29], 0, v43, s[16:17]
	s_cmp_lt_u32 s30, 20
	s_cbranch_scc1 .Lnsa_rank_done
	v_readlane_b32 s0, v32, 20
	v_readlane_b32 s1, v33, 20
	v_readlane_b32 s2, v35, 20
	v_readlane_b32 s3, v34, 20
	s_lshl_b64 s[26:27], -1, 21
	v_cmp_gt_f32_e64 s[4:5], s0, v32
	v_cmp_gt_f32_e64 s[6:7], s1, v33
	v_cmp_gt_f32_e64 s[8:9], s2, v35
	v_cmp_gt_f32_e64 s[16:17], s3, v34
	v_cmp_eq_f32_e64 s[18:19], s0, v32
	v_cmp_eq_f32_e64 s[20:21], s1, v33
	v_cmp_eq_f32_e64 s[22:23], s2, v35
	v_cmp_eq_f32_e64 s[24:25], s3, v34
	s_and_b64 s[18:19], s[18:19], s[26:27]
	s_or_b64 s[4:5], s[4:5], s[18:19]
	s_and_b64 s[20:21], s[20:21], s[26:27]
	s_or_b64 s[6:7], s[6:7], s[20:21]
	s_and_b64 s[22:23], s[22:23], s[26:27]
	s_or_b64 s[8:9], s[8:9], s[22:23]
	s_and_b64 s[24:25], s[24:25], s[26:27]
	s_or_b64 s[16:17], s[16:17], s[24:25]
	v_addc_co_u32_e64 v40, s[28:29], 0, v40, s[4:5]
	v_addc_co_u32_e64 v41, s[28:29], 0, v41, s[6:7]
	v_addc_co_u32_e64 v42, s[28:29], 0, v42, s[8:9]
	v_addc_co_u32_e64 v43, s[28:29], 0, v43, s[16:17]
	v_readlane_b32 s0, v32, 21
	v_readlane_b32 s1, v33, 21
	v_readlane_b32 s2, v35, 21
	v_readlane_b32 s3, v34, 21
	s_lshl_b64 s[26:27], -1, 22
	v_cmp_gt_f32_e64 s[4:5], s0, v32
	v_cmp_gt_f32_e64 s[6:7], s1, v33
	v_cmp_gt_f32_e64 s[8:9], s2, v35
	v_cmp_gt_f32_e64 s[16:17], s3, v34
	v_cmp_eq_f32_e64 s[18:19], s0, v32
	v_cmp_eq_f32_e64 s[20:21], s1, v33
	v_cmp_eq_f32_e64 s[22:23], s2, v35
	v_cmp_eq_f32_e64 s[24:25], s3, v34
	s_and_b64 s[18:19], s[18:19], s[26:27]
	s_or_b64 s[4:5], s[4:5], s[18:19]
	s_and_b64 s[20:21], s[20:21], s[26:27]
	s_or_b64 s[6:7], s[6:7], s[20:21]
	s_and_b64 s[22:23], s[22:23], s[26:27]
	s_or_b64 s[8:9], s[8:9], s[22:23]
	s_and_b64 s[24:25], s[24:25], s[26:27]
	s_or_b64 s[16:17], s[16:17], s[24:25]
	v_addc_co_u32_e64 v40, s[28:29], 0, v40, s[4:5]
	v_addc_co_u32_e64 v41, s[28:29], 0, v41, s[6:7]
	v_addc_co_u32_e64 v42, s[28:29], 0, v42, s[8:9]
	v_addc_co_u32_e64 v43, s[28:29], 0, v43, s[16:17]
	s_cmp_lt_u32 s30, 22
	s_cbranch_scc1 .Lnsa_rank_done
	v_readlane_b32 s0, v32, 22
	v_readlane_b32 s1, v33, 22
	v_readlane_b32 s2, v35, 22
	v_readlane_b32 s3, v34, 22
	s_lshl_b64 s[26:27], -1, 23
	v_cmp_gt_f32_e64 s[4:5], s0, v32
	v_cmp_gt_f32_e64 s[6:7], s1, v33
	v_cmp_gt_f32_e64 s[8:9], s2, v35
	v_cmp_gt_f32_e64 s[16:17], s3, v34
	v_cmp_eq_f32_e64 s[18:19], s0, v32
	v_cmp_eq_f32_e64 s[20:21], s1, v33
	v_cmp_eq_f32_e64 s[22:23], s2, v35
	v_cmp_eq_f32_e64 s[24:25], s3, v34
	s_and_b64 s[18:19], s[18:19], s[26:27]
	s_or_b64 s[4:5], s[4:5], s[18:19]
	s_and_b64 s[20:21], s[20:21], s[26:27]
	s_or_b64 s[6:7], s[6:7], s[20:21]
	s_and_b64 s[22:23], s[22:23], s[26:27]
	s_or_b64 s[8:9], s[8:9], s[22:23]
	s_and_b64 s[24:25], s[24:25], s[26:27]
	s_or_b64 s[16:17], s[16:17], s[24:25]
	v_addc_co_u32_e64 v40, s[28:29], 0, v40, s[4:5]
	v_addc_co_u32_e64 v41, s[28:29], 0, v41, s[6:7]
	v_addc_co_u32_e64 v42, s[28:29], 0, v42, s[8:9]
	v_addc_co_u32_e64 v43, s[28:29], 0, v43, s[16:17]
	v_readlane_b32 s0, v32, 23
	v_readlane_b32 s1, v33, 23
	v_readlane_b32 s2, v35, 23
	v_readlane_b32 s3, v34, 23
	s_lshl_b64 s[26:27], -1, 24
	v_cmp_gt_f32_e64 s[4:5], s0, v32
	v_cmp_gt_f32_e64 s[6:7], s1, v33
	v_cmp_gt_f32_e64 s[8:9], s2, v35
	v_cmp_gt_f32_e64 s[16:17], s3, v34
	v_cmp_eq_f32_e64 s[18:19], s0, v32
	v_cmp_eq_f32_e64 s[20:21], s1, v33
	v_cmp_eq_f32_e64 s[22:23], s2, v35
	v_cmp_eq_f32_e64 s[24:25], s3, v34
	s_and_b64 s[18:19], s[18:19], s[26:27]
	s_or_b64 s[4:5], s[4:5], s[18:19]
	s_and_b64 s[20:21], s[20:21], s[26:27]
	s_or_b64 s[6:7], s[6:7], s[20:21]
	s_and_b64 s[22:23], s[22:23], s[26:27]
	s_or_b64 s[8:9], s[8:9], s[22:23]
	s_and_b64 s[24:25], s[24:25], s[26:27]
	s_or_b64 s[16:17], s[16:17], s[24:25]
	v_addc_co_u32_e64 v40, s[28:29], 0, v40, s[4:5]
	v_addc_co_u32_e64 v41, s[28:29], 0, v41, s[6:7]
	v_addc_co_u32_e64 v42, s[28:29], 0, v42, s[8:9]
	v_addc_co_u32_e64 v43, s[28:29], 0, v43, s[16:17]
	s_cmp_lt_u32 s30, 24
	s_cbranch_scc1 .Lnsa_rank_done
	v_readlane_b32 s0, v32, 24
	v_readlane_b32 s1, v33, 24
	v_readlane_b32 s2, v35, 24
	v_readlane_b32 s3, v34, 24
	s_lshl_b64 s[26:27], -1, 25
	v_cmp_gt_f32_e64 s[4:5], s0, v32
	v_cmp_gt_f32_e64 s[6:7], s1, v33
	v_cmp_gt_f32_e64 s[8:9], s2, v35
	v_cmp_gt_f32_e64 s[16:17], s3, v34
	v_cmp_eq_f32_e64 s[18:19], s0, v32
	v_cmp_eq_f32_e64 s[20:21], s1, v33
	v_cmp_eq_f32_e64 s[22:23], s2, v35
	v_cmp_eq_f32_e64 s[24:25], s3, v34
	s_and_b64 s[18:19], s[18:19], s[26:27]
	s_or_b64 s[4:5], s[4:5], s[18:19]
	s_and_b64 s[20:21], s[20:21], s[26:27]
	s_or_b64 s[6:7], s[6:7], s[20:21]
	s_and_b64 s[22:23], s[22:23], s[26:27]
	s_or_b64 s[8:9], s[8:9], s[22:23]
	s_and_b64 s[24:25], s[24:25], s[26:27]
	s_or_b64 s[16:17], s[16:17], s[24:25]
	v_addc_co_u32_e64 v40, s[28:29], 0, v40, s[4:5]
	v_addc_co_u32_e64 v41, s[28:29], 0, v41, s[6:7]
	v_addc_co_u32_e64 v42, s[28:29], 0, v42, s[8:9]
	v_addc_co_u32_e64 v43, s[28:29], 0, v43, s[16:17]
	v_readlane_b32 s0, v32, 25
	v_readlane_b32 s1, v33, 25
	v_readlane_b32 s2, v35, 25
	v_readlane_b32 s3, v34, 25
	s_lshl_b64 s[26:27], -1, 26
	v_cmp_gt_f32_e64 s[4:5], s0, v32
	v_cmp_gt_f32_e64 s[6:7], s1, v33
	v_cmp_gt_f32_e64 s[8:9], s2, v35
	v_cmp_gt_f32_e64 s[16:17], s3, v34
	v_cmp_eq_f32_e64 s[18:19], s0, v32
	v_cmp_eq_f32_e64 s[20:21], s1, v33
	v_cmp_eq_f32_e64 s[22:23], s2, v35
	v_cmp_eq_f32_e64 s[24:25], s3, v34
	s_and_b64 s[18:19], s[18:19], s[26:27]
	s_or_b64 s[4:5], s[4:5], s[18:19]
	s_and_b64 s[20:21], s[20:21], s[26:27]
	s_or_b64 s[6:7], s[6:7], s[20:21]
	s_and_b64 s[22:23], s[22:23], s[26:27]
	s_or_b64 s[8:9], s[8:9], s[22:23]
	s_and_b64 s[24:25], s[24:25], s[26:27]
	s_or_b64 s[16:17], s[16:17], s[24:25]
	v_addc_co_u32_e64 v40, s[28:29], 0, v40, s[4:5]
	v_addc_co_u32_e64 v41, s[28:29], 0, v41, s[6:7]
	v_addc_co_u32_e64 v42, s[28:29], 0, v42, s[8:9]
	v_addc_co_u32_e64 v43, s[28:29], 0, v43, s[16:17]
	s_cmp_lt_u32 s30, 26
	s_cbranch_scc1 .Lnsa_rank_done
	v_readlane_b32 s0, v32, 26
	v_readlane_b32 s1, v33, 26
	v_readlane_b32 s2, v35, 26
	v_readlane_b32 s3, v34, 26
	s_lshl_b64 s[26:27], -1, 27
	v_cmp_gt_f32_e64 s[4:5], s0, v32
	v_cmp_gt_f32_e64 s[6:7], s1, v33
	v_cmp_gt_f32_e64 s[8:9], s2, v35
	v_cmp_gt_f32_e64 s[16:17], s3, v34
	v_cmp_eq_f32_e64 s[18:19], s0, v32
	v_cmp_eq_f32_e64 s[20:21], s1, v33
	v_cmp_eq_f32_e64 s[22:23], s2, v35
	v_cmp_eq_f32_e64 s[24:25], s3, v34
	s_and_b64 s[18:19], s[18:19], s[26:27]
	s_or_b64 s[4:5], s[4:5], s[18:19]
	s_and_b64 s[20:21], s[20:21], s[26:27]
	s_or_b64 s[6:7], s[6:7], s[20:21]
	s_and_b64 s[22:23], s[22:23], s[26:27]
	s_or_b64 s[8:9], s[8:9], s[22:23]
	s_and_b64 s[24:25], s[24:25], s[26:27]
	s_or_b64 s[16:17], s[16:17], s[24:25]
	v_addc_co_u32_e64 v40, s[28:29], 0, v40, s[4:5]
	v_addc_co_u32_e64 v41, s[28:29], 0, v41, s[6:7]
	v_addc_co_u32_e64 v42, s[28:29], 0, v42, s[8:9]
	v_addc_co_u32_e64 v43, s[28:29], 0, v43, s[16:17]
	v_readlane_b32 s0, v32, 27
	v_readlane_b32 s1, v33, 27
	v_readlane_b32 s2, v35, 27
	v_readlane_b32 s3, v34, 27
	s_lshl_b64 s[26:27], -1, 28
	v_cmp_gt_f32_e64 s[4:5], s0, v32
	v_cmp_gt_f32_e64 s[6:7], s1, v33
	v_cmp_gt_f32_e64 s[8:9], s2, v35
	v_cmp_gt_f32_e64 s[16:17], s3, v34
	v_cmp_eq_f32_e64 s[18:19], s0, v32
	v_cmp_eq_f32_e64 s[20:21], s1, v33
	v_cmp_eq_f32_e64 s[22:23], s2, v35
	v_cmp_eq_f32_e64 s[24:25], s3, v34
	s_and_b64 s[18:19], s[18:19], s[26:27]
	s_or_b64 s[4:5], s[4:5], s[18:19]
	s_and_b64 s[20:21], s[20:21], s[26:27]
	s_or_b64 s[6:7], s[6:7], s[20:21]
	s_and_b64 s[22:23], s[22:23], s[26:27]
	s_or_b64 s[8:9], s[8:9], s[22:23]
	s_and_b64 s[24:25], s[24:25], s[26:27]
	s_or_b64 s[16:17], s[16:17], s[24:25]
	v_addc_co_u32_e64 v40, s[28:29], 0, v40, s[4:5]
	v_addc_co_u32_e64 v41, s[28:29], 0, v41, s[6:7]
	v_addc_co_u32_e64 v42, s[28:29], 0, v42, s[8:9]
	v_addc_co_u32_e64 v43, s[28:29], 0, v43, s[16:17]
	s_cmp_lt_u32 s30, 28
	s_cbranch_scc1 .Lnsa_rank_done
	v_readlane_b32 s0, v32, 28
	v_readlane_b32 s1, v33, 28
	v_readlane_b32 s2, v35, 28
	v_readlane_b32 s3, v34, 28
	s_lshl_b64 s[26:27], -1, 29
	v_cmp_gt_f32_e64 s[4:5], s0, v32
	v_cmp_gt_f32_e64 s[6:7], s1, v33
	v_cmp_gt_f32_e64 s[8:9], s2, v35
	v_cmp_gt_f32_e64 s[16:17], s3, v34
	v_cmp_eq_f32_e64 s[18:19], s0, v32
	v_cmp_eq_f32_e64 s[20:21], s1, v33
	v_cmp_eq_f32_e64 s[22:23], s2, v35
	v_cmp_eq_f32_e64 s[24:25], s3, v34
	s_and_b64 s[18:19], s[18:19], s[26:27]
	s_or_b64 s[4:5], s[4:5], s[18:19]
	s_and_b64 s[20:21], s[20:21], s[26:27]
	s_or_b64 s[6:7], s[6:7], s[20:21]
	s_and_b64 s[22:23], s[22:23], s[26:27]
	s_or_b64 s[8:9], s[8:9], s[22:23]
	s_and_b64 s[24:25], s[24:25], s[26:27]
	s_or_b64 s[16:17], s[16:17], s[24:25]
	v_addc_co_u32_e64 v40, s[28:29], 0, v40, s[4:5]
	v_addc_co_u32_e64 v41, s[28:29], 0, v41, s[6:7]
	v_addc_co_u32_e64 v42, s[28:29], 0, v42, s[8:9]
	v_addc_co_u32_e64 v43, s[28:29], 0, v43, s[16:17]
	v_readlane_b32 s0, v32, 29
	v_readlane_b32 s1, v33, 29
	v_readlane_b32 s2, v35, 29
	v_readlane_b32 s3, v34, 29
	s_lshl_b64 s[26:27], -1, 30
	v_cmp_gt_f32_e64 s[4:5], s0, v32
	v_cmp_gt_f32_e64 s[6:7], s1, v33
	v_cmp_gt_f32_e64 s[8:9], s2, v35
	v_cmp_gt_f32_e64 s[16:17], s3, v34
	v_cmp_eq_f32_e64 s[18:19], s0, v32
	v_cmp_eq_f32_e64 s[20:21], s1, v33
	v_cmp_eq_f32_e64 s[22:23], s2, v35
	v_cmp_eq_f32_e64 s[24:25], s3, v34
	s_and_b64 s[18:19], s[18:19], s[26:27]
	s_or_b64 s[4:5], s[4:5], s[18:19]
	s_and_b64 s[20:21], s[20:21], s[26:27]
	s_or_b64 s[6:7], s[6:7], s[20:21]
	s_and_b64 s[22:23], s[22:23], s[26:27]
	s_or_b64 s[8:9], s[8:9], s[22:23]
	s_and_b64 s[24:25], s[24:25], s[26:27]
	s_or_b64 s[16:17], s[16:17], s[24:25]
	v_addc_co_u32_e64 v40, s[28:29], 0, v40, s[4:5]
	v_addc_co_u32_e64 v41, s[28:29], 0, v41, s[6:7]
	v_addc_co_u32_e64 v42, s[28:29], 0, v42, s[8:9]
	v_addc_co_u32_e64 v43, s[28:29], 0, v43, s[16:17]
	s_cmp_lt_u32 s30, 30
	s_cbranch_scc1 .Lnsa_rank_done
	v_readlane_b32 s0, v32, 30
	v_readlane_b32 s1, v33, 30
	v_readlane_b32 s2, v35, 30
	v_readlane_b32 s3, v34, 30
	s_lshl_b64 s[26:27], -1, 31
	v_cmp_gt_f32_e64 s[4:5], s0, v32
	v_cmp_gt_f32_e64 s[6:7], s1, v33
	v_cmp_gt_f32_e64 s[8:9], s2, v35
	v_cmp_gt_f32_e64 s[16:17], s3, v34
	v_cmp_eq_f32_e64 s[18:19], s0, v32
	v_cmp_eq_f32_e64 s[20:21], s1, v33
	v_cmp_eq_f32_e64 s[22:23], s2, v35
	v_cmp_eq_f32_e64 s[24:25], s3, v34
	s_and_b64 s[18:19], s[18:19], s[26:27]
	s_or_b64 s[4:5], s[4:5], s[18:19]
	s_and_b64 s[20:21], s[20:21], s[26:27]
	s_or_b64 s[6:7], s[6:7], s[20:21]
	s_and_b64 s[22:23], s[22:23], s[26:27]
	s_or_b64 s[8:9], s[8:9], s[22:23]
	s_and_b64 s[24:25], s[24:25], s[26:27]
	s_or_b64 s[16:17], s[16:17], s[24:25]
	v_addc_co_u32_e64 v40, s[28:29], 0, v40, s[4:5]
	v_addc_co_u32_e64 v41, s[28:29], 0, v41, s[6:7]
	v_addc_co_u32_e64 v42, s[28:29], 0, v42, s[8:9]
	v_addc_co_u32_e64 v43, s[28:29], 0, v43, s[16:17]
	v_readlane_b32 s0, v32, 31
	v_readlane_b32 s1, v33, 31
	v_readlane_b32 s2, v35, 31
	v_readlane_b32 s3, v34, 31
	s_lshl_b64 s[26:27], -1, 32
	v_cmp_gt_f32_e64 s[4:5], s0, v32
	v_cmp_gt_f32_e64 s[6:7], s1, v33
	v_cmp_gt_f32_e64 s[8:9], s2, v35
	v_cmp_gt_f32_e64 s[16:17], s3, v34
	v_cmp_eq_f32_e64 s[18:19], s0, v32
	v_cmp_eq_f32_e64 s[20:21], s1, v33
	v_cmp_eq_f32_e64 s[22:23], s2, v35
	v_cmp_eq_f32_e64 s[24:25], s3, v34
	s_and_b64 s[18:19], s[18:19], s[26:27]
	s_or_b64 s[4:5], s[4:5], s[18:19]
	s_and_b64 s[20:21], s[20:21], s[26:27]
	s_or_b64 s[6:7], s[6:7], s[20:21]
	s_and_b64 s[22:23], s[22:23], s[26:27]
	s_or_b64 s[8:9], s[8:9], s[22:23]
	s_and_b64 s[24:25], s[24:25], s[26:27]
	s_or_b64 s[16:17], s[16:17], s[24:25]
	v_addc_co_u32_e64 v40, s[28:29], 0, v40, s[4:5]
	v_addc_co_u32_e64 v41, s[28:29], 0, v41, s[6:7]
	v_addc_co_u32_e64 v42, s[28:29], 0, v42, s[8:9]
	v_addc_co_u32_e64 v43, s[28:29], 0, v43, s[16:17]
	s_cmp_lt_u32 s30, 32
	s_cbranch_scc1 .Lnsa_rank_done
	v_readlane_b32 s0, v32, 32
	v_readlane_b32 s1, v33, 32
	v_readlane_b32 s2, v35, 32
	v_readlane_b32 s3, v34, 32
	s_lshl_b64 s[26:27], -1, 33
	v_cmp_gt_f32_e64 s[4:5], s0, v32
	v_cmp_gt_f32_e64 s[6:7], s1, v33
	v_cmp_gt_f32_e64 s[8:9], s2, v35
	v_cmp_gt_f32_e64 s[16:17], s3, v34
	v_cmp_eq_f32_e64 s[18:19], s0, v32
	v_cmp_eq_f32_e64 s[20:21], s1, v33
	v_cmp_eq_f32_e64 s[22:23], s2, v35
	v_cmp_eq_f32_e64 s[24:25], s3, v34
	s_and_b64 s[18:19], s[18:19], s[26:27]
	s_or_b64 s[4:5], s[4:5], s[18:19]
	s_and_b64 s[20:21], s[20:21], s[26:27]
	s_or_b64 s[6:7], s[6:7], s[20:21]
	s_and_b64 s[22:23], s[22:23], s[26:27]
	s_or_b64 s[8:9], s[8:9], s[22:23]
	s_and_b64 s[24:25], s[24:25], s[26:27]
	s_or_b64 s[16:17], s[16:17], s[24:25]
	v_addc_co_u32_e64 v40, s[28:29], 0, v40, s[4:5]
	v_addc_co_u32_e64 v41, s[28:29], 0, v41, s[6:7]
	v_addc_co_u32_e64 v42, s[28:29], 0, v42, s[8:9]
	v_addc_co_u32_e64 v43, s[28:29], 0, v43, s[16:17]
	v_readlane_b32 s0, v32, 33
	v_readlane_b32 s1, v33, 33
	v_readlane_b32 s2, v35, 33
	v_readlane_b32 s3, v34, 33
	s_lshl_b64 s[26:27], -1, 34
	v_cmp_gt_f32_e64 s[4:5], s0, v32
	v_cmp_gt_f32_e64 s[6:7], s1, v33
	v_cmp_gt_f32_e64 s[8:9], s2, v35
	v_cmp_gt_f32_e64 s[16:17], s3, v34
	v_cmp_eq_f32_e64 s[18:19], s0, v32
	v_cmp_eq_f32_e64 s[20:21], s1, v33
	v_cmp_eq_f32_e64 s[22:23], s2, v35
	v_cmp_eq_f32_e64 s[24:25], s3, v34
	s_and_b64 s[18:19], s[18:19], s[26:27]
	s_or_b64 s[4:5], s[4:5], s[18:19]
	s_and_b64 s[20:21], s[20:21], s[26:27]
	s_or_b64 s[6:7], s[6:7], s[20:21]
	s_and_b64 s[22:23], s[22:23], s[26:27]
	s_or_b64 s[8:9], s[8:9], s[22:23]
	s_and_b64 s[24:25], s[24:25], s[26:27]
	s_or_b64 s[16:17], s[16:17], s[24:25]
	v_addc_co_u32_e64 v40, s[28:29], 0, v40, s[4:5]
	v_addc_co_u32_e64 v41, s[28:29], 0, v41, s[6:7]
	v_addc_co_u32_e64 v42, s[28:29], 0, v42, s[8:9]
	v_addc_co_u32_e64 v43, s[28:29], 0, v43, s[16:17]
	s_cmp_lt_u32 s30, 34
	s_cbranch_scc1 .Lnsa_rank_done
	v_readlane_b32 s0, v32, 34
	v_readlane_b32 s1, v33, 34
	v_readlane_b32 s2, v35, 34
	v_readlane_b32 s3, v34, 34
	s_lshl_b64 s[26:27], -1, 35
	v_cmp_gt_f32_e64 s[4:5], s0, v32
	v_cmp_gt_f32_e64 s[6:7], s1, v33
	v_cmp_gt_f32_e64 s[8:9], s2, v35
	v_cmp_gt_f32_e64 s[16:17], s3, v34
	v_cmp_eq_f32_e64 s[18:19], s0, v32
	v_cmp_eq_f32_e64 s[20:21], s1, v33
	v_cmp_eq_f32_e64 s[22:23], s2, v35
	v_cmp_eq_f32_e64 s[24:25], s3, v34
	s_and_b64 s[18:19], s[18:19], s[26:27]
	s_or_b64 s[4:5], s[4:5], s[18:19]
	s_and_b64 s[20:21], s[20:21], s[26:27]
	s_or_b64 s[6:7], s[6:7], s[20:21]
	s_and_b64 s[22:23], s[22:23], s[26:27]
	s_or_b64 s[8:9], s[8:9], s[22:23]
	s_and_b64 s[24:25], s[24:25], s[26:27]
	s_or_b64 s[16:17], s[16:17], s[24:25]
	v_addc_co_u32_e64 v40, s[28:29], 0, v40, s[4:5]
	v_addc_co_u32_e64 v41, s[28:29], 0, v41, s[6:7]
	v_addc_co_u32_e64 v42, s[28:29], 0, v42, s[8:9]
	v_addc_co_u32_e64 v43, s[28:29], 0, v43, s[16:17]
	v_readlane_b32 s0, v32, 35
	v_readlane_b32 s1, v33, 35
	v_readlane_b32 s2, v35, 35
	v_readlane_b32 s3, v34, 35
	s_lshl_b64 s[26:27], -1, 36
	v_cmp_gt_f32_e64 s[4:5], s0, v32
	v_cmp_gt_f32_e64 s[6:7], s1, v33
	v_cmp_gt_f32_e64 s[8:9], s2, v35
	v_cmp_gt_f32_e64 s[16:17], s3, v34
	v_cmp_eq_f32_e64 s[18:19], s0, v32
	v_cmp_eq_f32_e64 s[20:21], s1, v33
	v_cmp_eq_f32_e64 s[22:23], s2, v35
	v_cmp_eq_f32_e64 s[24:25], s3, v34
	s_and_b64 s[18:19], s[18:19], s[26:27]
	s_or_b64 s[4:5], s[4:5], s[18:19]
	s_and_b64 s[20:21], s[20:21], s[26:27]
	s_or_b64 s[6:7], s[6:7], s[20:21]
	s_and_b64 s[22:23], s[22:23], s[26:27]
	s_or_b64 s[8:9], s[8:9], s[22:23]
	s_and_b64 s[24:25], s[24:25], s[26:27]
	s_or_b64 s[16:17], s[16:17], s[24:25]
	v_addc_co_u32_e64 v40, s[28:29], 0, v40, s[4:5]
	v_addc_co_u32_e64 v41, s[28:29], 0, v41, s[6:7]
	v_addc_co_u32_e64 v42, s[28:29], 0, v42, s[8:9]
	v_addc_co_u32_e64 v43, s[28:29], 0, v43, s[16:17]
	s_cmp_lt_u32 s30, 36
	s_cbranch_scc1 .Lnsa_rank_done
	v_readlane_b32 s0, v32, 36
	v_readlane_b32 s1, v33, 36
	v_readlane_b32 s2, v35, 36
	v_readlane_b32 s3, v34, 36
	s_lshl_b64 s[26:27], -1, 37
	v_cmp_gt_f32_e64 s[4:5], s0, v32
	v_cmp_gt_f32_e64 s[6:7], s1, v33
	v_cmp_gt_f32_e64 s[8:9], s2, v35
	v_cmp_gt_f32_e64 s[16:17], s3, v34
	v_cmp_eq_f32_e64 s[18:19], s0, v32
	v_cmp_eq_f32_e64 s[20:21], s1, v33
	v_cmp_eq_f32_e64 s[22:23], s2, v35
	v_cmp_eq_f32_e64 s[24:25], s3, v34
	s_and_b64 s[18:19], s[18:19], s[26:27]
	s_or_b64 s[4:5], s[4:5], s[18:19]
	s_and_b64 s[20:21], s[20:21], s[26:27]
	s_or_b64 s[6:7], s[6:7], s[20:21]
	s_and_b64 s[22:23], s[22:23], s[26:27]
	s_or_b64 s[8:9], s[8:9], s[22:23]
	s_and_b64 s[24:25], s[24:25], s[26:27]
	s_or_b64 s[16:17], s[16:17], s[24:25]
	v_addc_co_u32_e64 v40, s[28:29], 0, v40, s[4:5]
	v_addc_co_u32_e64 v41, s[28:29], 0, v41, s[6:7]
	v_addc_co_u32_e64 v42, s[28:29], 0, v42, s[8:9]
	v_addc_co_u32_e64 v43, s[28:29], 0, v43, s[16:17]
	v_readlane_b32 s0, v32, 37
	v_readlane_b32 s1, v33, 37
	v_readlane_b32 s2, v35, 37
	v_readlane_b32 s3, v34, 37
	s_lshl_b64 s[26:27], -1, 38
	v_cmp_gt_f32_e64 s[4:5], s0, v32
	v_cmp_gt_f32_e64 s[6:7], s1, v33
	v_cmp_gt_f32_e64 s[8:9], s2, v35
	v_cmp_gt_f32_e64 s[16:17], s3, v34
	v_cmp_eq_f32_e64 s[18:19], s0, v32
	v_cmp_eq_f32_e64 s[20:21], s1, v33
	v_cmp_eq_f32_e64 s[22:23], s2, v35
	v_cmp_eq_f32_e64 s[24:25], s3, v34
	s_and_b64 s[18:19], s[18:19], s[26:27]
	s_or_b64 s[4:5], s[4:5], s[18:19]
	s_and_b64 s[20:21], s[20:21], s[26:27]
	s_or_b64 s[6:7], s[6:7], s[20:21]
	s_and_b64 s[22:23], s[22:23], s[26:27]
	s_or_b64 s[8:9], s[8:9], s[22:23]
	s_and_b64 s[24:25], s[24:25], s[26:27]
	s_or_b64 s[16:17], s[16:17], s[24:25]
	v_addc_co_u32_e64 v40, s[28:29], 0, v40, s[4:5]
	v_addc_co_u32_e64 v41, s[28:29], 0, v41, s[6:7]
	v_addc_co_u32_e64 v42, s[28:29], 0, v42, s[8:9]
	v_addc_co_u32_e64 v43, s[28:29], 0, v43, s[16:17]
	s_cmp_lt_u32 s30, 38
	s_cbranch_scc1 .Lnsa_rank_done
	v_readlane_b32 s0, v32, 38
	v_readlane_b32 s1, v33, 38
	v_readlane_b32 s2, v35, 38
	v_readlane_b32 s3, v34, 38
	s_lshl_b64 s[26:27], -1, 39
	v_cmp_gt_f32_e64 s[4:5], s0, v32
	v_cmp_gt_f32_e64 s[6:7], s1, v33
	v_cmp_gt_f32_e64 s[8:9], s2, v35
	v_cmp_gt_f32_e64 s[16:17], s3, v34
	v_cmp_eq_f32_e64 s[18:19], s0, v32
	v_cmp_eq_f32_e64 s[20:21], s1, v33
	v_cmp_eq_f32_e64 s[22:23], s2, v35
	v_cmp_eq_f32_e64 s[24:25], s3, v34
	s_and_b64 s[18:19], s[18:19], s[26:27]
	s_or_b64 s[4:5], s[4:5], s[18:19]
	s_and_b64 s[20:21], s[20:21], s[26:27]
	s_or_b64 s[6:7], s[6:7], s[20:21]
	s_and_b64 s[22:23], s[22:23], s[26:27]
	s_or_b64 s[8:9], s[8:9], s[22:23]
	s_and_b64 s[24:25], s[24:25], s[26:27]
	s_or_b64 s[16:17], s[16:17], s[24:25]
	v_addc_co_u32_e64 v40, s[28:29], 0, v40, s[4:5]
	v_addc_co_u32_e64 v41, s[28:29], 0, v41, s[6:7]
	v_addc_co_u32_e64 v42, s[28:29], 0, v42, s[8:9]
	v_addc_co_u32_e64 v43, s[28:29], 0, v43, s[16:17]
	v_readlane_b32 s0, v32, 39
	v_readlane_b32 s1, v33, 39
	v_readlane_b32 s2, v35, 39
	v_readlane_b32 s3, v34, 39
	s_lshl_b64 s[26:27], -1, 40
	v_cmp_gt_f32_e64 s[4:5], s0, v32
	v_cmp_gt_f32_e64 s[6:7], s1, v33
	v_cmp_gt_f32_e64 s[8:9], s2, v35
	v_cmp_gt_f32_e64 s[16:17], s3, v34
	v_cmp_eq_f32_e64 s[18:19], s0, v32
	v_cmp_eq_f32_e64 s[20:21], s1, v33
	v_cmp_eq_f32_e64 s[22:23], s2, v35
	v_cmp_eq_f32_e64 s[24:25], s3, v34
	s_and_b64 s[18:19], s[18:19], s[26:27]
	s_or_b64 s[4:5], s[4:5], s[18:19]
	s_and_b64 s[20:21], s[20:21], s[26:27]
	s_or_b64 s[6:7], s[6:7], s[20:21]
	s_and_b64 s[22:23], s[22:23], s[26:27]
	s_or_b64 s[8:9], s[8:9], s[22:23]
	s_and_b64 s[24:25], s[24:25], s[26:27]
	s_or_b64 s[16:17], s[16:17], s[24:25]
	v_addc_co_u32_e64 v40, s[28:29], 0, v40, s[4:5]
	v_addc_co_u32_e64 v41, s[28:29], 0, v41, s[6:7]
	v_addc_co_u32_e64 v42, s[28:29], 0, v42, s[8:9]
	v_addc_co_u32_e64 v43, s[28:29], 0, v43, s[16:17]
	s_cmp_lt_u32 s30, 40
	s_cbranch_scc1 .Lnsa_rank_done
	v_readlane_b32 s0, v32, 40
	v_readlane_b32 s1, v33, 40
	v_readlane_b32 s2, v35, 40
	v_readlane_b32 s3, v34, 40
	s_lshl_b64 s[26:27], -1, 41
	v_cmp_gt_f32_e64 s[4:5], s0, v32
	v_cmp_gt_f32_e64 s[6:7], s1, v33
	v_cmp_gt_f32_e64 s[8:9], s2, v35
	v_cmp_gt_f32_e64 s[16:17], s3, v34
	v_cmp_eq_f32_e64 s[18:19], s0, v32
	v_cmp_eq_f32_e64 s[20:21], s1, v33
	v_cmp_eq_f32_e64 s[22:23], s2, v35
	v_cmp_eq_f32_e64 s[24:25], s3, v34
	s_and_b64 s[18:19], s[18:19], s[26:27]
	s_or_b64 s[4:5], s[4:5], s[18:19]
	s_and_b64 s[20:21], s[20:21], s[26:27]
	s_or_b64 s[6:7], s[6:7], s[20:21]
	s_and_b64 s[22:23], s[22:23], s[26:27]
	s_or_b64 s[8:9], s[8:9], s[22:23]
	s_and_b64 s[24:25], s[24:25], s[26:27]
	s_or_b64 s[16:17], s[16:17], s[24:25]
	v_addc_co_u32_e64 v40, s[28:29], 0, v40, s[4:5]
	v_addc_co_u32_e64 v41, s[28:29], 0, v41, s[6:7]
	v_addc_co_u32_e64 v42, s[28:29], 0, v42, s[8:9]
	v_addc_co_u32_e64 v43, s[28:29], 0, v43, s[16:17]
	v_readlane_b32 s0, v32, 41
	v_readlane_b32 s1, v33, 41
	v_readlane_b32 s2, v35, 41
	v_readlane_b32 s3, v34, 41
	s_lshl_b64 s[26:27], -1, 42
	v_cmp_gt_f32_e64 s[4:5], s0, v32
	v_cmp_gt_f32_e64 s[6:7], s1, v33
	v_cmp_gt_f32_e64 s[8:9], s2, v35
	v_cmp_gt_f32_e64 s[16:17], s3, v34
	v_cmp_eq_f32_e64 s[18:19], s0, v32
	v_cmp_eq_f32_e64 s[20:21], s1, v33
	v_cmp_eq_f32_e64 s[22:23], s2, v35
	v_cmp_eq_f32_e64 s[24:25], s3, v34
	s_and_b64 s[18:19], s[18:19], s[26:27]
	s_or_b64 s[4:5], s[4:5], s[18:19]
	s_and_b64 s[20:21], s[20:21], s[26:27]
	s_or_b64 s[6:7], s[6:7], s[20:21]
	s_and_b64 s[22:23], s[22:23], s[26:27]
	s_or_b64 s[8:9], s[8:9], s[22:23]
	s_and_b64 s[24:25], s[24:25], s[26:27]
	s_or_b64 s[16:17], s[16:17], s[24:25]
	v_addc_co_u32_e64 v40, s[28:29], 0, v40, s[4:5]
	v_addc_co_u32_e64 v41, s[28:29], 0, v41, s[6:7]
	v_addc_co_u32_e64 v42, s[28:29], 0, v42, s[8:9]
	v_addc_co_u32_e64 v43, s[28:29], 0, v43, s[16:17]
	s_cmp_lt_u32 s30, 42
	s_cbranch_scc1 .Lnsa_rank_done
	v_readlane_b32 s0, v32, 42
	v_readlane_b32 s1, v33, 42
	v_readlane_b32 s2, v35, 42
	v_readlane_b32 s3, v34, 42
	s_lshl_b64 s[26:27], -1, 43
	v_cmp_gt_f32_e64 s[4:5], s0, v32
	v_cmp_gt_f32_e64 s[6:7], s1, v33
	v_cmp_gt_f32_e64 s[8:9], s2, v35
	v_cmp_gt_f32_e64 s[16:17], s3, v34
	v_cmp_eq_f32_e64 s[18:19], s0, v32
	v_cmp_eq_f32_e64 s[20:21], s1, v33
	v_cmp_eq_f32_e64 s[22:23], s2, v35
	v_cmp_eq_f32_e64 s[24:25], s3, v34
	s_and_b64 s[18:19], s[18:19], s[26:27]
	s_or_b64 s[4:5], s[4:5], s[18:19]
	s_and_b64 s[20:21], s[20:21], s[26:27]
	s_or_b64 s[6:7], s[6:7], s[20:21]
	s_and_b64 s[22:23], s[22:23], s[26:27]
	s_or_b64 s[8:9], s[8:9], s[22:23]
	s_and_b64 s[24:25], s[24:25], s[26:27]
	s_or_b64 s[16:17], s[16:17], s[24:25]
	v_addc_co_u32_e64 v40, s[28:29], 0, v40, s[4:5]
	v_addc_co_u32_e64 v41, s[28:29], 0, v41, s[6:7]
	v_addc_co_u32_e64 v42, s[28:29], 0, v42, s[8:9]
	v_addc_co_u32_e64 v43, s[28:29], 0, v43, s[16:17]
	v_readlane_b32 s0, v32, 43
	v_readlane_b32 s1, v33, 43
	v_readlane_b32 s2, v35, 43
	v_readlane_b32 s3, v34, 43
	s_lshl_b64 s[26:27], -1, 44
	v_cmp_gt_f32_e64 s[4:5], s0, v32
	v_cmp_gt_f32_e64 s[6:7], s1, v33
	v_cmp_gt_f32_e64 s[8:9], s2, v35
	v_cmp_gt_f32_e64 s[16:17], s3, v34
	v_cmp_eq_f32_e64 s[18:19], s0, v32
	v_cmp_eq_f32_e64 s[20:21], s1, v33
	v_cmp_eq_f32_e64 s[22:23], s2, v35
	v_cmp_eq_f32_e64 s[24:25], s3, v34
	s_and_b64 s[18:19], s[18:19], s[26:27]
	s_or_b64 s[4:5], s[4:5], s[18:19]
	s_and_b64 s[20:21], s[20:21], s[26:27]
	s_or_b64 s[6:7], s[6:7], s[20:21]
	s_and_b64 s[22:23], s[22:23], s[26:27]
	s_or_b64 s[8:9], s[8:9], s[22:23]
	s_and_b64 s[24:25], s[24:25], s[26:27]
	s_or_b64 s[16:17], s[16:17], s[24:25]
	v_addc_co_u32_e64 v40, s[28:29], 0, v40, s[4:5]
	v_addc_co_u32_e64 v41, s[28:29], 0, v41, s[6:7]
	v_addc_co_u32_e64 v42, s[28:29], 0, v42, s[8:9]
	v_addc_co_u32_e64 v43, s[28:29], 0, v43, s[16:17]
	s_cmp_lt_u32 s30, 44
	s_cbranch_scc1 .Lnsa_rank_done
	v_readlane_b32 s0, v32, 44
	v_readlane_b32 s1, v33, 44
	v_readlane_b32 s2, v35, 44
	v_readlane_b32 s3, v34, 44
	s_lshl_b64 s[26:27], -1, 45
	v_cmp_gt_f32_e64 s[4:5], s0, v32
	v_cmp_gt_f32_e64 s[6:7], s1, v33
	v_cmp_gt_f32_e64 s[8:9], s2, v35
	v_cmp_gt_f32_e64 s[16:17], s3, v34
	v_cmp_eq_f32_e64 s[18:19], s0, v32
	v_cmp_eq_f32_e64 s[20:21], s1, v33
	v_cmp_eq_f32_e64 s[22:23], s2, v35
	v_cmp_eq_f32_e64 s[24:25], s3, v34
	s_and_b64 s[18:19], s[18:19], s[26:27]
	s_or_b64 s[4:5], s[4:5], s[18:19]
	s_and_b64 s[20:21], s[20:21], s[26:27]
	s_or_b64 s[6:7], s[6:7], s[20:21]
	s_and_b64 s[22:23], s[22:23], s[26:27]
	s_or_b64 s[8:9], s[8:9], s[22:23]
	s_and_b64 s[24:25], s[24:25], s[26:27]
	s_or_b64 s[16:17], s[16:17], s[24:25]
	v_addc_co_u32_e64 v40, s[28:29], 0, v40, s[4:5]
	v_addc_co_u32_e64 v41, s[28:29], 0, v41, s[6:7]
	v_addc_co_u32_e64 v42, s[28:29], 0, v42, s[8:9]
	v_addc_co_u32_e64 v43, s[28:29], 0, v43, s[16:17]
	v_readlane_b32 s0, v32, 45
	v_readlane_b32 s1, v33, 45
	v_readlane_b32 s2, v35, 45
	v_readlane_b32 s3, v34, 45
	s_lshl_b64 s[26:27], -1, 46
	v_cmp_gt_f32_e64 s[4:5], s0, v32
	v_cmp_gt_f32_e64 s[6:7], s1, v33
	v_cmp_gt_f32_e64 s[8:9], s2, v35
	v_cmp_gt_f32_e64 s[16:17], s3, v34
	v_cmp_eq_f32_e64 s[18:19], s0, v32
	v_cmp_eq_f32_e64 s[20:21], s1, v33
	v_cmp_eq_f32_e64 s[22:23], s2, v35
	v_cmp_eq_f32_e64 s[24:25], s3, v34
	s_and_b64 s[18:19], s[18:19], s[26:27]
	s_or_b64 s[4:5], s[4:5], s[18:19]
	s_and_b64 s[20:21], s[20:21], s[26:27]
	s_or_b64 s[6:7], s[6:7], s[20:21]
	s_and_b64 s[22:23], s[22:23], s[26:27]
	s_or_b64 s[8:9], s[8:9], s[22:23]
	s_and_b64 s[24:25], s[24:25], s[26:27]
	s_or_b64 s[16:17], s[16:17], s[24:25]
	v_addc_co_u32_e64 v40, s[28:29], 0, v40, s[4:5]
	v_addc_co_u32_e64 v41, s[28:29], 0, v41, s[6:7]
	v_addc_co_u32_e64 v42, s[28:29], 0, v42, s[8:9]
	v_addc_co_u32_e64 v43, s[28:29], 0, v43, s[16:17]
	s_cmp_lt_u32 s30, 46
	s_cbranch_scc1 .Lnsa_rank_done
	v_readlane_b32 s0, v32, 46
	v_readlane_b32 s1, v33, 46
	v_readlane_b32 s2, v35, 46
	v_readlane_b32 s3, v34, 46
	s_lshl_b64 s[26:27], -1, 47
	v_cmp_gt_f32_e64 s[4:5], s0, v32
	v_cmp_gt_f32_e64 s[6:7], s1, v33
	v_cmp_gt_f32_e64 s[8:9], s2, v35
	v_cmp_gt_f32_e64 s[16:17], s3, v34
	v_cmp_eq_f32_e64 s[18:19], s0, v32
	v_cmp_eq_f32_e64 s[20:21], s1, v33
	v_cmp_eq_f32_e64 s[22:23], s2, v35
	v_cmp_eq_f32_e64 s[24:25], s3, v34
	s_and_b64 s[18:19], s[18:19], s[26:27]
	s_or_b64 s[4:5], s[4:5], s[18:19]
	s_and_b64 s[20:21], s[20:21], s[26:27]
	s_or_b64 s[6:7], s[6:7], s[20:21]
	s_and_b64 s[22:23], s[22:23], s[26:27]
	s_or_b64 s[8:9], s[8:9], s[22:23]
	s_and_b64 s[24:25], s[24:25], s[26:27]
	s_or_b64 s[16:17], s[16:17], s[24:25]
	v_addc_co_u32_e64 v40, s[28:29], 0, v40, s[4:5]
	v_addc_co_u32_e64 v41, s[28:29], 0, v41, s[6:7]
	v_addc_co_u32_e64 v42, s[28:29], 0, v42, s[8:9]
	v_addc_co_u32_e64 v43, s[28:29], 0, v43, s[16:17]
	v_readlane_b32 s0, v32, 47
	v_readlane_b32 s1, v33, 47
	v_readlane_b32 s2, v35, 47
	v_readlane_b32 s3, v34, 47
	s_lshl_b64 s[26:27], -1, 48
	v_cmp_gt_f32_e64 s[4:5], s0, v32
	v_cmp_gt_f32_e64 s[6:7], s1, v33
	v_cmp_gt_f32_e64 s[8:9], s2, v35
	v_cmp_gt_f32_e64 s[16:17], s3, v34
	v_cmp_eq_f32_e64 s[18:19], s0, v32
	v_cmp_eq_f32_e64 s[20:21], s1, v33
	v_cmp_eq_f32_e64 s[22:23], s2, v35
	v_cmp_eq_f32_e64 s[24:25], s3, v34
	s_and_b64 s[18:19], s[18:19], s[26:27]
	s_or_b64 s[4:5], s[4:5], s[18:19]
	s_and_b64 s[20:21], s[20:21], s[26:27]
	s_or_b64 s[6:7], s[6:7], s[20:21]
	s_and_b64 s[22:23], s[22:23], s[26:27]
	s_or_b64 s[8:9], s[8:9], s[22:23]
	s_and_b64 s[24:25], s[24:25], s[26:27]
	s_or_b64 s[16:17], s[16:17], s[24:25]
	v_addc_co_u32_e64 v40, s[28:29], 0, v40, s[4:5]
	v_addc_co_u32_e64 v41, s[28:29], 0, v41, s[6:7]
	v_addc_co_u32_e64 v42, s[28:29], 0, v42, s[8:9]
	v_addc_co_u32_e64 v43, s[28:29], 0, v43, s[16:17]
	s_cmp_lt_u32 s30, 48
	s_cbranch_scc1 .Lnsa_rank_done
	v_readlane_b32 s0, v32, 48
	v_readlane_b32 s1, v33, 48
	v_readlane_b32 s2, v35, 48
	v_readlane_b32 s3, v34, 48
	s_lshl_b64 s[26:27], -1, 49
	v_cmp_gt_f32_e64 s[4:5], s0, v32
	v_cmp_gt_f32_e64 s[6:7], s1, v33
	v_cmp_gt_f32_e64 s[8:9], s2, v35
	v_cmp_gt_f32_e64 s[16:17], s3, v34
	v_cmp_eq_f32_e64 s[18:19], s0, v32
	v_cmp_eq_f32_e64 s[20:21], s1, v33
	v_cmp_eq_f32_e64 s[22:23], s2, v35
	v_cmp_eq_f32_e64 s[24:25], s3, v34
	s_and_b64 s[18:19], s[18:19], s[26:27]
	s_or_b64 s[4:5], s[4:5], s[18:19]
	s_and_b64 s[20:21], s[20:21], s[26:27]
	s_or_b64 s[6:7], s[6:7], s[20:21]
	s_and_b64 s[22:23], s[22:23], s[26:27]
	s_or_b64 s[8:9], s[8:9], s[22:23]
	s_and_b64 s[24:25], s[24:25], s[26:27]
	s_or_b64 s[16:17], s[16:17], s[24:25]
	v_addc_co_u32_e64 v40, s[28:29], 0, v40, s[4:5]
	v_addc_co_u32_e64 v41, s[28:29], 0, v41, s[6:7]
	v_addc_co_u32_e64 v42, s[28:29], 0, v42, s[8:9]
	v_addc_co_u32_e64 v43, s[28:29], 0, v43, s[16:17]
	v_readlane_b32 s0, v32, 49
	v_readlane_b32 s1, v33, 49
	v_readlane_b32 s2, v35, 49
	v_readlane_b32 s3, v34, 49
	s_lshl_b64 s[26:27], -1, 50
	v_cmp_gt_f32_e64 s[4:5], s0, v32
	v_cmp_gt_f32_e64 s[6:7], s1, v33
	v_cmp_gt_f32_e64 s[8:9], s2, v35
	v_cmp_gt_f32_e64 s[16:17], s3, v34
	v_cmp_eq_f32_e64 s[18:19], s0, v32
	v_cmp_eq_f32_e64 s[20:21], s1, v33
	v_cmp_eq_f32_e64 s[22:23], s2, v35
	v_cmp_eq_f32_e64 s[24:25], s3, v34
	s_and_b64 s[18:19], s[18:19], s[26:27]
	s_or_b64 s[4:5], s[4:5], s[18:19]
	s_and_b64 s[20:21], s[20:21], s[26:27]
	s_or_b64 s[6:7], s[6:7], s[20:21]
	s_and_b64 s[22:23], s[22:23], s[26:27]
	s_or_b64 s[8:9], s[8:9], s[22:23]
	s_and_b64 s[24:25], s[24:25], s[26:27]
	s_or_b64 s[16:17], s[16:17], s[24:25]
	v_addc_co_u32_e64 v40, s[28:29], 0, v40, s[4:5]
	v_addc_co_u32_e64 v41, s[28:29], 0, v41, s[6:7]
	v_addc_co_u32_e64 v42, s[28:29], 0, v42, s[8:9]
	v_addc_co_u32_e64 v43, s[28:29], 0, v43, s[16:17]
	s_cmp_lt_u32 s30, 50
	s_cbranch_scc1 .Lnsa_rank_done
	v_readlane_b32 s0, v32, 50
	v_readlane_b32 s1, v33, 50
	v_readlane_b32 s2, v35, 50
	v_readlane_b32 s3, v34, 50
	s_lshl_b64 s[26:27], -1, 51
	v_cmp_gt_f32_e64 s[4:5], s0, v32
	v_cmp_gt_f32_e64 s[6:7], s1, v33
	v_cmp_gt_f32_e64 s[8:9], s2, v35
	v_cmp_gt_f32_e64 s[16:17], s3, v34
	v_cmp_eq_f32_e64 s[18:19], s0, v32
	v_cmp_eq_f32_e64 s[20:21], s1, v33
	v_cmp_eq_f32_e64 s[22:23], s2, v35
	v_cmp_eq_f32_e64 s[24:25], s3, v34
	s_and_b64 s[18:19], s[18:19], s[26:27]
	s_or_b64 s[4:5], s[4:5], s[18:19]
	s_and_b64 s[20:21], s[20:21], s[26:27]
	s_or_b64 s[6:7], s[6:7], s[20:21]
	s_and_b64 s[22:23], s[22:23], s[26:27]
	s_or_b64 s[8:9], s[8:9], s[22:23]
	s_and_b64 s[24:25], s[24:25], s[26:27]
	s_or_b64 s[16:17], s[16:17], s[24:25]
	v_addc_co_u32_e64 v40, s[28:29], 0, v40, s[4:5]
	v_addc_co_u32_e64 v41, s[28:29], 0, v41, s[6:7]
	v_addc_co_u32_e64 v42, s[28:29], 0, v42, s[8:9]
	v_addc_co_u32_e64 v43, s[28:29], 0, v43, s[16:17]
	v_readlane_b32 s0, v32, 51
	v_readlane_b32 s1, v33, 51
	v_readlane_b32 s2, v35, 51
	v_readlane_b32 s3, v34, 51
	s_lshl_b64 s[26:27], -1, 52
	v_cmp_gt_f32_e64 s[4:5], s0, v32
	v_cmp_gt_f32_e64 s[6:7], s1, v33
	v_cmp_gt_f32_e64 s[8:9], s2, v35
	v_cmp_gt_f32_e64 s[16:17], s3, v34
	v_cmp_eq_f32_e64 s[18:19], s0, v32
	v_cmp_eq_f32_e64 s[20:21], s1, v33
	v_cmp_eq_f32_e64 s[22:23], s2, v35
	v_cmp_eq_f32_e64 s[24:25], s3, v34
	s_and_b64 s[18:19], s[18:19], s[26:27]
	s_or_b64 s[4:5], s[4:5], s[18:19]
	s_and_b64 s[20:21], s[20:21], s[26:27]
	s_or_b64 s[6:7], s[6:7], s[20:21]
	s_and_b64 s[22:23], s[22:23], s[26:27]
	s_or_b64 s[8:9], s[8:9], s[22:23]
	s_and_b64 s[24:25], s[24:25], s[26:27]
	s_or_b64 s[16:17], s[16:17], s[24:25]
	v_addc_co_u32_e64 v40, s[28:29], 0, v40, s[4:5]
	v_addc_co_u32_e64 v41, s[28:29], 0, v41, s[6:7]
	v_addc_co_u32_e64 v42, s[28:29], 0, v42, s[8:9]
	v_addc_co_u32_e64 v43, s[28:29], 0, v43, s[16:17]
	s_cmp_lt_u32 s30, 52
	s_cbranch_scc1 .Lnsa_rank_done
	v_readlane_b32 s0, v32, 52
	v_readlane_b32 s1, v33, 52
	v_readlane_b32 s2, v35, 52
	v_readlane_b32 s3, v34, 52
	s_lshl_b64 s[26:27], -1, 53
	v_cmp_gt_f32_e64 s[4:5], s0, v32
	v_cmp_gt_f32_e64 s[6:7], s1, v33
	v_cmp_gt_f32_e64 s[8:9], s2, v35
	v_cmp_gt_f32_e64 s[16:17], s3, v34
	v_cmp_eq_f32_e64 s[18:19], s0, v32
	v_cmp_eq_f32_e64 s[20:21], s1, v33
	v_cmp_eq_f32_e64 s[22:23], s2, v35
	v_cmp_eq_f32_e64 s[24:25], s3, v34
	s_and_b64 s[18:19], s[18:19], s[26:27]
	s_or_b64 s[4:5], s[4:5], s[18:19]
	s_and_b64 s[20:21], s[20:21], s[26:27]
	s_or_b64 s[6:7], s[6:7], s[20:21]
	s_and_b64 s[22:23], s[22:23], s[26:27]
	s_or_b64 s[8:9], s[8:9], s[22:23]
	s_and_b64 s[24:25], s[24:25], s[26:27]
	s_or_b64 s[16:17], s[16:17], s[24:25]
	v_addc_co_u32_e64 v40, s[28:29], 0, v40, s[4:5]
	v_addc_co_u32_e64 v41, s[28:29], 0, v41, s[6:7]
	v_addc_co_u32_e64 v42, s[28:29], 0, v42, s[8:9]
	v_addc_co_u32_e64 v43, s[28:29], 0, v43, s[16:17]
	v_readlane_b32 s0, v32, 53
	v_readlane_b32 s1, v33, 53
	v_readlane_b32 s2, v35, 53
	v_readlane_b32 s3, v34, 53
	s_lshl_b64 s[26:27], -1, 54
	v_cmp_gt_f32_e64 s[4:5], s0, v32
	v_cmp_gt_f32_e64 s[6:7], s1, v33
	v_cmp_gt_f32_e64 s[8:9], s2, v35
	v_cmp_gt_f32_e64 s[16:17], s3, v34
	v_cmp_eq_f32_e64 s[18:19], s0, v32
	v_cmp_eq_f32_e64 s[20:21], s1, v33
	v_cmp_eq_f32_e64 s[22:23], s2, v35
	v_cmp_eq_f32_e64 s[24:25], s3, v34
	s_and_b64 s[18:19], s[18:19], s[26:27]
	s_or_b64 s[4:5], s[4:5], s[18:19]
	s_and_b64 s[20:21], s[20:21], s[26:27]
	s_or_b64 s[6:7], s[6:7], s[20:21]
	s_and_b64 s[22:23], s[22:23], s[26:27]
	s_or_b64 s[8:9], s[8:9], s[22:23]
	s_and_b64 s[24:25], s[24:25], s[26:27]
	s_or_b64 s[16:17], s[16:17], s[24:25]
	v_addc_co_u32_e64 v40, s[28:29], 0, v40, s[4:5]
	v_addc_co_u32_e64 v41, s[28:29], 0, v41, s[6:7]
	v_addc_co_u32_e64 v42, s[28:29], 0, v42, s[8:9]
	v_addc_co_u32_e64 v43, s[28:29], 0, v43, s[16:17]
	s_cmp_lt_u32 s30, 54
	s_cbranch_scc1 .Lnsa_rank_done
	v_readlane_b32 s0, v32, 54
	v_readlane_b32 s1, v33, 54
	v_readlane_b32 s2, v35, 54
	v_readlane_b32 s3, v34, 54
	s_lshl_b64 s[26:27], -1, 55
	v_cmp_gt_f32_e64 s[4:5], s0, v32
	v_cmp_gt_f32_e64 s[6:7], s1, v33
	v_cmp_gt_f32_e64 s[8:9], s2, v35
	v_cmp_gt_f32_e64 s[16:17], s3, v34
	v_cmp_eq_f32_e64 s[18:19], s0, v32
	v_cmp_eq_f32_e64 s[20:21], s1, v33
	v_cmp_eq_f32_e64 s[22:23], s2, v35
	v_cmp_eq_f32_e64 s[24:25], s3, v34
	s_and_b64 s[18:19], s[18:19], s[26:27]
	s_or_b64 s[4:5], s[4:5], s[18:19]
	s_and_b64 s[20:21], s[20:21], s[26:27]
	s_or_b64 s[6:7], s[6:7], s[20:21]
	s_and_b64 s[22:23], s[22:23], s[26:27]
	s_or_b64 s[8:9], s[8:9], s[22:23]
	s_and_b64 s[24:25], s[24:25], s[26:27]
	s_or_b64 s[16:17], s[16:17], s[24:25]
	v_addc_co_u32_e64 v40, s[28:29], 0, v40, s[4:5]
	v_addc_co_u32_e64 v41, s[28:29], 0, v41, s[6:7]
	v_addc_co_u32_e64 v42, s[28:29], 0, v42, s[8:9]
	v_addc_co_u32_e64 v43, s[28:29], 0, v43, s[16:17]
	v_readlane_b32 s0, v32, 55
	v_readlane_b32 s1, v33, 55
	v_readlane_b32 s2, v35, 55
	v_readlane_b32 s3, v34, 55
	s_lshl_b64 s[26:27], -1, 56
	v_cmp_gt_f32_e64 s[4:5], s0, v32
	v_cmp_gt_f32_e64 s[6:7], s1, v33
	v_cmp_gt_f32_e64 s[8:9], s2, v35
	v_cmp_gt_f32_e64 s[16:17], s3, v34
	v_cmp_eq_f32_e64 s[18:19], s0, v32
	v_cmp_eq_f32_e64 s[20:21], s1, v33
	v_cmp_eq_f32_e64 s[22:23], s2, v35
	v_cmp_eq_f32_e64 s[24:25], s3, v34
	s_and_b64 s[18:19], s[18:19], s[26:27]
	s_or_b64 s[4:5], s[4:5], s[18:19]
	s_and_b64 s[20:21], s[20:21], s[26:27]
	s_or_b64 s[6:7], s[6:7], s[20:21]
	s_and_b64 s[22:23], s[22:23], s[26:27]
	s_or_b64 s[8:9], s[8:9], s[22:23]
	s_and_b64 s[24:25], s[24:25], s[26:27]
	s_or_b64 s[16:17], s[16:17], s[24:25]
	v_addc_co_u32_e64 v40, s[28:29], 0, v40, s[4:5]
	v_addc_co_u32_e64 v41, s[28:29], 0, v41, s[6:7]
	v_addc_co_u32_e64 v42, s[28:29], 0, v42, s[8:9]
	v_addc_co_u32_e64 v43, s[28:29], 0, v43, s[16:17]
	s_cmp_lt_u32 s30, 56
	s_cbranch_scc1 .Lnsa_rank_done
	v_readlane_b32 s0, v32, 56
	v_readlane_b32 s1, v33, 56
	v_readlane_b32 s2, v35, 56
	v_readlane_b32 s3, v34, 56
	s_lshl_b64 s[26:27], -1, 57
	v_cmp_gt_f32_e64 s[4:5], s0, v32
	v_cmp_gt_f32_e64 s[6:7], s1, v33
	v_cmp_gt_f32_e64 s[8:9], s2, v35
	v_cmp_gt_f32_e64 s[16:17], s3, v34
	v_cmp_eq_f32_e64 s[18:19], s0, v32
	v_cmp_eq_f32_e64 s[20:21], s1, v33
	v_cmp_eq_f32_e64 s[22:23], s2, v35
	v_cmp_eq_f32_e64 s[24:25], s3, v34
	s_and_b64 s[18:19], s[18:19], s[26:27]
	s_or_b64 s[4:5], s[4:5], s[18:19]
	s_and_b64 s[20:21], s[20:21], s[26:27]
	s_or_b64 s[6:7], s[6:7], s[20:21]
	s_and_b64 s[22:23], s[22:23], s[26:27]
	s_or_b64 s[8:9], s[8:9], s[22:23]
	s_and_b64 s[24:25], s[24:25], s[26:27]
	s_or_b64 s[16:17], s[16:17], s[24:25]
	v_addc_co_u32_e64 v40, s[28:29], 0, v40, s[4:5]
	v_addc_co_u32_e64 v41, s[28:29], 0, v41, s[6:7]
	v_addc_co_u32_e64 v42, s[28:29], 0, v42, s[8:9]
	v_addc_co_u32_e64 v43, s[28:29], 0, v43, s[16:17]
	v_readlane_b32 s0, v32, 57
	v_readlane_b32 s1, v33, 57
	v_readlane_b32 s2, v35, 57
	v_readlane_b32 s3, v34, 57
	s_lshl_b64 s[26:27], -1, 58
	v_cmp_gt_f32_e64 s[4:5], s0, v32
	v_cmp_gt_f32_e64 s[6:7], s1, v33
	v_cmp_gt_f32_e64 s[8:9], s2, v35
	v_cmp_gt_f32_e64 s[16:17], s3, v34
	v_cmp_eq_f32_e64 s[18:19], s0, v32
	v_cmp_eq_f32_e64 s[20:21], s1, v33
	v_cmp_eq_f32_e64 s[22:23], s2, v35
	v_cmp_eq_f32_e64 s[24:25], s3, v34
	s_and_b64 s[18:19], s[18:19], s[26:27]
	s_or_b64 s[4:5], s[4:5], s[18:19]
	s_and_b64 s[20:21], s[20:21], s[26:27]
	s_or_b64 s[6:7], s[6:7], s[20:21]
	s_and_b64 s[22:23], s[22:23], s[26:27]
	s_or_b64 s[8:9], s[8:9], s[22:23]
	s_and_b64 s[24:25], s[24:25], s[26:27]
	s_or_b64 s[16:17], s[16:17], s[24:25]
	v_addc_co_u32_e64 v40, s[28:29], 0, v40, s[4:5]
	v_addc_co_u32_e64 v41, s[28:29], 0, v41, s[6:7]
	v_addc_co_u32_e64 v42, s[28:29], 0, v42, s[8:9]
	v_addc_co_u32_e64 v43, s[28:29], 0, v43, s[16:17]
	s_cmp_lt_u32 s30, 58
	s_cbranch_scc1 .Lnsa_rank_done
	v_readlane_b32 s0, v32, 58
	v_readlane_b32 s1, v33, 58
	v_readlane_b32 s2, v35, 58
	v_readlane_b32 s3, v34, 58
	s_lshl_b64 s[26:27], -1, 59
	v_cmp_gt_f32_e64 s[4:5], s0, v32
	v_cmp_gt_f32_e64 s[6:7], s1, v33
	v_cmp_gt_f32_e64 s[8:9], s2, v35
	v_cmp_gt_f32_e64 s[16:17], s3, v34
	v_cmp_eq_f32_e64 s[18:19], s0, v32
	v_cmp_eq_f32_e64 s[20:21], s1, v33
	v_cmp_eq_f32_e64 s[22:23], s2, v35
	v_cmp_eq_f32_e64 s[24:25], s3, v34
	s_and_b64 s[18:19], s[18:19], s[26:27]
	s_or_b64 s[4:5], s[4:5], s[18:19]
	s_and_b64 s[20:21], s[20:21], s[26:27]
	s_or_b64 s[6:7], s[6:7], s[20:21]
	s_and_b64 s[22:23], s[22:23], s[26:27]
	s_or_b64 s[8:9], s[8:9], s[22:23]
	s_and_b64 s[24:25], s[24:25], s[26:27]
	s_or_b64 s[16:17], s[16:17], s[24:25]
	v_addc_co_u32_e64 v40, s[28:29], 0, v40, s[4:5]
	v_addc_co_u32_e64 v41, s[28:29], 0, v41, s[6:7]
	v_addc_co_u32_e64 v42, s[28:29], 0, v42, s[8:9]
	v_addc_co_u32_e64 v43, s[28:29], 0, v43, s[16:17]
	v_readlane_b32 s0, v32, 59
	v_readlane_b32 s1, v33, 59
	v_readlane_b32 s2, v35, 59
	v_readlane_b32 s3, v34, 59
	s_lshl_b64 s[26:27], -1, 60
	v_cmp_gt_f32_e64 s[4:5], s0, v32
	v_cmp_gt_f32_e64 s[6:7], s1, v33
	v_cmp_gt_f32_e64 s[8:9], s2, v35
	v_cmp_gt_f32_e64 s[16:17], s3, v34
	v_cmp_eq_f32_e64 s[18:19], s0, v32
	v_cmp_eq_f32_e64 s[20:21], s1, v33
	v_cmp_eq_f32_e64 s[22:23], s2, v35
	v_cmp_eq_f32_e64 s[24:25], s3, v34
	s_and_b64 s[18:19], s[18:19], s[26:27]
	s_or_b64 s[4:5], s[4:5], s[18:19]
	s_and_b64 s[20:21], s[20:21], s[26:27]
	s_or_b64 s[6:7], s[6:7], s[20:21]
	s_and_b64 s[22:23], s[22:23], s[26:27]
	s_or_b64 s[8:9], s[8:9], s[22:23]
	s_and_b64 s[24:25], s[24:25], s[26:27]
	s_or_b64 s[16:17], s[16:17], s[24:25]
	v_addc_co_u32_e64 v40, s[28:29], 0, v40, s[4:5]
	v_addc_co_u32_e64 v41, s[28:29], 0, v41, s[6:7]
	v_addc_co_u32_e64 v42, s[28:29], 0, v42, s[8:9]
	v_addc_co_u32_e64 v43, s[28:29], 0, v43, s[16:17]
	s_cmp_lt_u32 s30, 60
	s_cbranch_scc1 .Lnsa_rank_done
	v_readlane_b32 s0, v32, 60
	v_readlane_b32 s1, v33, 60
	v_readlane_b32 s2, v35, 60
	v_readlane_b32 s3, v34, 60
	s_lshl_b64 s[26:27], -1, 61
	v_cmp_gt_f32_e64 s[4:5], s0, v32
	v_cmp_gt_f32_e64 s[6:7], s1, v33
	v_cmp_gt_f32_e64 s[8:9], s2, v35
	v_cmp_gt_f32_e64 s[16:17], s3, v34
	v_cmp_eq_f32_e64 s[18:19], s0, v32
	v_cmp_eq_f32_e64 s[20:21], s1, v33
	v_cmp_eq_f32_e64 s[22:23], s2, v35
	v_cmp_eq_f32_e64 s[24:25], s3, v34
	s_and_b64 s[18:19], s[18:19], s[26:27]
	s_or_b64 s[4:5], s[4:5], s[18:19]
	s_and_b64 s[20:21], s[20:21], s[26:27]
	s_or_b64 s[6:7], s[6:7], s[20:21]
	s_and_b64 s[22:23], s[22:23], s[26:27]
	s_or_b64 s[8:9], s[8:9], s[22:23]
	s_and_b64 s[24:25], s[24:25], s[26:27]
	s_or_b64 s[16:17], s[16:17], s[24:25]
	v_addc_co_u32_e64 v40, s[28:29], 0, v40, s[4:5]
	v_addc_co_u32_e64 v41, s[28:29], 0, v41, s[6:7]
	v_addc_co_u32_e64 v42, s[28:29], 0, v42, s[8:9]
	v_addc_co_u32_e64 v43, s[28:29], 0, v43, s[16:17]
	v_readlane_b32 s0, v32, 61
	v_readlane_b32 s1, v33, 61
	v_readlane_b32 s2, v35, 61
	v_readlane_b32 s3, v34, 61
	s_lshl_b64 s[26:27], -1, 62
	v_cmp_gt_f32_e64 s[4:5], s0, v32
	v_cmp_gt_f32_e64 s[6:7], s1, v33
	v_cmp_gt_f32_e64 s[8:9], s2, v35
	v_cmp_gt_f32_e64 s[16:17], s3, v34
	v_cmp_eq_f32_e64 s[18:19], s0, v32
	v_cmp_eq_f32_e64 s[20:21], s1, v33
	v_cmp_eq_f32_e64 s[22:23], s2, v35
	v_cmp_eq_f32_e64 s[24:25], s3, v34
	s_and_b64 s[18:19], s[18:19], s[26:27]
	s_or_b64 s[4:5], s[4:5], s[18:19]
	s_and_b64 s[20:21], s[20:21], s[26:27]
	s_or_b64 s[6:7], s[6:7], s[20:21]
	s_and_b64 s[22:23], s[22:23], s[26:27]
	s_or_b64 s[8:9], s[8:9], s[22:23]
	s_and_b64 s[24:25], s[24:25], s[26:27]
	s_or_b64 s[16:17], s[16:17], s[24:25]
	v_addc_co_u32_e64 v40, s[28:29], 0, v40, s[4:5]
	v_addc_co_u32_e64 v41, s[28:29], 0, v41, s[6:7]
	v_addc_co_u32_e64 v42, s[28:29], 0, v42, s[8:9]
	v_addc_co_u32_e64 v43, s[28:29], 0, v43, s[16:17]
	s_cmp_lt_u32 s30, 62
	s_cbranch_scc1 .Lnsa_rank_done
	v_readlane_b32 s0, v32, 62
	v_readlane_b32 s1, v33, 62
	v_readlane_b32 s2, v35, 62
	v_readlane_b32 s3, v34, 62
	s_lshl_b64 s[26:27], -1, 63
	v_cmp_gt_f32_e64 s[4:5], s0, v32
	v_cmp_gt_f32_e64 s[6:7], s1, v33
	v_cmp_gt_f32_e64 s[8:9], s2, v35
	v_cmp_gt_f32_e64 s[16:17], s3, v34
	v_cmp_eq_f32_e64 s[18:19], s0, v32
	v_cmp_eq_f32_e64 s[20:21], s1, v33
	v_cmp_eq_f32_e64 s[22:23], s2, v35
	v_cmp_eq_f32_e64 s[24:25], s3, v34
	s_and_b64 s[18:19], s[18:19], s[26:27]
	s_or_b64 s[4:5], s[4:5], s[18:19]
	s_and_b64 s[20:21], s[20:21], s[26:27]
	s_or_b64 s[6:7], s[6:7], s[20:21]
	s_and_b64 s[22:23], s[22:23], s[26:27]
	s_or_b64 s[8:9], s[8:9], s[22:23]
	s_and_b64 s[24:25], s[24:25], s[26:27]
	s_or_b64 s[16:17], s[16:17], s[24:25]
	v_addc_co_u32_e64 v40, s[28:29], 0, v40, s[4:5]
	v_addc_co_u32_e64 v41, s[28:29], 0, v41, s[6:7]
	v_addc_co_u32_e64 v42, s[28:29], 0, v42, s[8:9]
	v_addc_co_u32_e64 v43, s[28:29], 0, v43, s[16:17]
	v_readlane_b32 s0, v32, 63
	v_readlane_b32 s1, v33, 63
	v_readlane_b32 s2, v35, 63
	v_readlane_b32 s3, v34, 63
	v_cmp_gt_f32_e64 s[4:5], s0, v32
	v_cmp_gt_f32_e64 s[6:7], s1, v33
	v_cmp_gt_f32_e64 s[8:9], s2, v35
	v_cmp_gt_f32_e64 s[16:17], s3, v34
	v_addc_co_u32_e64 v40, s[28:29], 0, v40, s[4:5]
	v_addc_co_u32_e64 v41, s[28:29], 0, v41, s[6:7]
	v_addc_co_u32_e64 v42, s[28:29], 0, v42, s[8:9]
	v_addc_co_u32_e64 v43, s[28:29], 0, v43, s[16:17]

.LBB0_594:
	s_cmp_lg_u32 s63, 0
	s_cbranch_scc1 .Lnsa_wr1
	s_waitcnt vmcnt(1)
	ds_write_b128 v117, v[16:19]
	s_waitcnt vmcnt(0)
	ds_write_b128 v116, v[20:23] offset:38912
	s_branch .LBB0_595
.Lnsa_wr1:
	s_waitcnt vmcnt(1)
	ds_write_b128 v117, v[16:19] offset:9472
	s_waitcnt vmcnt(0)
	ds_write_b128 v116, v[20:23] offset:48128
